# speedup vs baseline: 1.0058x; 1.0058x over previous
; #define G_STAGE(bufoff, gbase, voff) do { _Pragma("unroll") for (int _i = 0; _i < 2; ++_i) \
;         __builtin_amdgcn_global_load_lds((const unsigned*)((const char*)(gbase) + (voff)[_i]), (LAS unsigned*)(lds + (bufoff) + ldsw + _i * 8192), 16, 0, 0); } while (0)
; #define G_LDA(dst, b, h) do { _Pragma("unroll") for (int m = 0; m < 4; ++m) _Pragma("unroll") for (int k = 0; k < 2; ++k) dst[m][k] = *(const LAS bf16x8*)(lds + G_SA(b, h) + aoff + m * 2048 + k * 1024); } while (0)
; #define G_LDB(dst, b, h) do { _Pragma("unroll") for (int n = 0; n < 2; ++n) _Pragma("unroll") for (int k = 0; k < 2; ++k) dst[n][k] = *(const LAS bf16x8*)(lds + G_SB(b, h) + boff + n * 2048 + k * 1024); } while (0)
; #define G_MMA(ai, bj, At, Bt) do { __builtin_amdgcn_s_setprio(1); _Pragma("unroll") for (int m = 0; m < 4; ++m) _Pragma("unroll") for (int n = 0; n < 2; ++n) _Pragma("unroll") for (int k = 0; k < 2; ++k) \
;         acc[ai][bj][m][n] = __builtin_amdgcn_mfma_f32_16x16x32_bf16(Bt[n][k], At[m][k], acc[ai][bj][m][n], 0, 0, 0); __builtin_amdgcn_s_setprio(0); } while (0)
; #define G_WAIT_V(n) asm volatile("s_waitcnt vmcnt(" #n ")" ::: "memory")
; #define G_WAIT_L(n) asm volatile("s_waitcnt lgkmcnt(" #n ")" ::: "memory")
; #define G_BAR __builtin_amdgcn_s_barrier()
; #define G_SCHED __builtin_amdgcn_sched_barrier(0)
; template <class J>
; DI void gemm_phase(LAS unsigned char* lds, const J& job) {
;     ...
;       G_LDB(B0, 0, 0); G_SCHED; G_LDA(At, 0, 0); G_STAGE(G_SA(1, 1), a1 + hstepA, voffA);
;       G_WAIT_L(8); G_BAR; G_WAIT_L(0); G_MMA(0, 0, At, B0); G_BAR; G_SCHED;
;       G_LDB(B1, 0, 1); G_STAGE(G_SB(0, 0), b2, voffB);
;       G_BAR; G_WAIT_L(0); G_MMA(0, 1, At, B1); G_BAR;
;       G_LDA(At, 0, 1); G_STAGE(G_SA(0, 0), a2, voffA);
;       G_BAR; G_WAIT_L(0); G_MMA(1, 0, At, B0); G_BAR; G_SCHED;
;       G_STAGE(G_SB(0, 1), b2 + hstepB, voffB);
;       G_WAIT_V(6); G_BAR; G_MMA(1, 1, At, B1); G_BAR;
.LBB0_42:
	s_add_i32 s2, s84, 0x100
	ds_read_b128 v[128:131], v221
	ds_read_b128 v[132:135], v221 offset:1024
	ds_read_b128 v[136:139], v221 offset:2048
	ds_read_b128 v[140:143], v221 offset:3072
	s_add_u32 s0, s21, s0
	s_addc_u32 s1, s23, 0
	ds_read_b128 v[154:157], v163
	ds_read_b128 v[164:167], v163 offset:1024
	ds_read_b128 v[168:171], v163 offset:2048
	ds_read_b128 v[172:175], v163 offset:3072
	ds_read_b128 v[176:179], v163 offset:4096
	ds_read_b128 v[180:183], v163 offset:5120
	ds_read_b128 v[184:187], v163 offset:6144
	ds_read_b128 v[188:191], v163 offset:7168
	s_waitcnt lgkmcnt(8)
	s_barrier
	s_waitcnt lgkmcnt(0)
	v_mfma_f32_16x16x32_bf16 v[124:127], v[128:131], v[154:157], v[124:127]
	v_mfma_f32_16x16x32_bf16 v[120:123], v[136:139], v[154:157], v[120:123]
	v_mfma_f32_16x16x32_bf16 v[108:111], v[128:131], v[168:171], v[108:111]
	v_mfma_f32_16x16x32_bf16 v[104:107], v[136:139], v[168:171], v[104:107]
	v_mfma_f32_16x16x32_bf16 v[92:95], v[128:131], v[176:179], v[92:95]
	v_mfma_f32_16x16x32_bf16 v[88:91], v[136:139], v[176:179], v[88:91]
	v_mfma_f32_16x16x32_bf16 v[76:79], v[128:131], v[184:187], v[76:79]
	v_mfma_f32_16x16x32_bf16 v[72:75], v[136:139], v[184:187], v[72:75]
	v_mfma_f32_16x16x32_bf16 v[124:127], v[132:135], v[164:167], v[124:127]
	v_mfma_f32_16x16x32_bf16 v[120:123], v[140:143], v[164:167], v[120:123]
	v_mfma_f32_16x16x32_bf16 v[108:111], v[132:135], v[172:175], v[108:111]
	v_mfma_f32_16x16x32_bf16 v[104:107], v[140:143], v[172:175], v[104:107]
	v_mfma_f32_16x16x32_bf16 v[92:95], v[132:135], v[180:183], v[92:95]
	v_mfma_f32_16x16x32_bf16 v[88:91], v[140:143], v[180:183], v[88:91]
	v_mfma_f32_16x16x32_bf16 v[76:79], v[132:135], v[188:191], v[76:79]
	v_mfma_f32_16x16x32_bf16 v[72:75], v[140:143], v[188:191], v[72:75]
	s_barrier
	s_add_i32 m0, s25, 0xc000
	s_nop 0
	global_load_lds_dwordx4 v148, s[0:1]
	s_add_i32 m0, s25, 0xe000
	s_nop 0
	global_load_lds_dwordx4 v150, s[0:1]
	s_add_i32 s54, s85, 0x100
	s_add_i32 s0, s2, s14
	ds_read_b128 v[192:195], v221 offset:16384
	ds_read_b128 v[196:199], v221 offset:17408
	ds_read_b128 v[200:203], v221 offset:18432
	ds_read_b128 v[204:207], v221 offset:19456
	s_mov_b32 m0, s0
	s_nop 0
	global_load_lds_dwordx4 v146, s[78:79]
	s_add_i32 m0, s0, 0x2000
	s_nop 0
	global_load_lds_dwordx4 v152, s[78:79]
	s_barrier
	s_waitcnt lgkmcnt(0)
	v_mfma_f32_16x16x32_bf16 v[116:119], v[192:195], v[154:157], v[116:119]
	v_mfma_f32_16x16x32_bf16 v[112:115], v[200:203], v[154:157], v[112:115]
	v_mfma_f32_16x16x32_bf16 v[100:103], v[192:195], v[168:171], v[100:103]
	v_mfma_f32_16x16x32_bf16 v[96:99], v[200:203], v[168:171], v[96:99]
	v_mfma_f32_16x16x32_bf16 v[84:87], v[192:195], v[176:179], v[84:87]
	v_mfma_f32_16x16x32_bf16 v[80:83], v[200:203], v[176:179], v[80:83]
	v_mfma_f32_16x16x32_bf16 v[68:71], v[192:195], v[184:187], v[68:71]
	v_mfma_f32_16x16x32_bf16 v[64:67], v[200:203], v[184:187], v[64:67]
	v_mfma_f32_16x16x32_bf16 v[116:119], v[196:199], v[164:167], v[116:119]
	v_mfma_f32_16x16x32_bf16 v[112:115], v[204:207], v[164:167], v[112:115]
	v_mfma_f32_16x16x32_bf16 v[100:103], v[196:199], v[172:175], v[100:103]
	v_mfma_f32_16x16x32_bf16 v[96:99], v[204:207], v[172:175], v[96:99]
	v_mfma_f32_16x16x32_bf16 v[84:87], v[196:199], v[180:183], v[84:87]
	v_mfma_f32_16x16x32_bf16 v[80:83], v[204:207], v[180:183], v[80:83]
	v_mfma_f32_16x16x32_bf16 v[68:71], v[196:199], v[188:191], v[68:71]
	v_mfma_f32_16x16x32_bf16 v[64:67], v[204:207], v[188:191], v[64:67]
	s_mov_b32 m0, s25
	s_barrier
	ds_read_b128 v[154:157], v163 offset:16384
	ds_read_b128 v[164:167], v163 offset:17408
	ds_read_b128 v[168:171], v163 offset:18432
	ds_read_b128 v[172:175], v163 offset:19456
	ds_read_b128 v[176:179], v163 offset:20480
	ds_read_b128 v[180:183], v163 offset:21504
	ds_read_b128 v[184:187], v163 offset:22528
	ds_read_b128 v[188:191], v163 offset:23552
	global_load_lds_dwordx4 v148, s[76:77]
	s_mov_b32 m0, s36
	s_nop 0
	global_load_lds_dwordx4 v150, s[76:77]
	s_barrier
	s_waitcnt lgkmcnt(0)
	v_mfma_f32_16x16x32_bf16 v[60:63], v[128:131], v[154:157], v[60:63]
	v_mfma_f32_16x16x32_bf16 v[56:59], v[136:139], v[154:157], v[56:59]
	v_mfma_f32_16x16x32_bf16 v[44:47], v[128:131], v[168:171], v[44:47]
	v_mfma_f32_16x16x32_bf16 v[40:43], v[136:139], v[168:171], v[40:43]
	v_mfma_f32_16x16x32_bf16 v[28:31], v[128:131], v[176:179], v[28:31]
	v_mfma_f32_16x16x32_bf16 v[24:27], v[136:139], v[176:179], v[24:27]
	v_mfma_f32_16x16x32_bf16 v[20:23], v[128:131], v[184:187], v[20:23]
	v_mfma_f32_16x16x32_bf16 v[12:15], v[136:139], v[184:187], v[12:15]
	v_mfma_f32_16x16x32_bf16 v[60:63], v[132:135], v[164:167], v[60:63]
	v_mfma_f32_16x16x32_bf16 v[56:59], v[140:143], v[164:167], v[56:59]
	v_mfma_f32_16x16x32_bf16 v[44:47], v[132:135], v[172:175], v[44:47]
	v_mfma_f32_16x16x32_bf16 v[40:43], v[140:143], v[172:175], v[40:43]
	v_mfma_f32_16x16x32_bf16 v[28:31], v[132:135], v[180:183], v[28:31]
	v_mfma_f32_16x16x32_bf16 v[24:27], v[140:143], v[180:183], v[24:27]
	v_mfma_f32_16x16x32_bf16 v[20:23], v[132:135], v[188:191], v[20:23]
	v_mfma_f32_16x16x32_bf16 v[12:15], v[140:143], v[188:191], v[12:15]
	s_barrier
	s_add_u32 s0, s78, 0x80000
	s_addc_u32 s1, s79, 0
	s_add_i32 s2, s54, s14
	s_mov_b32 m0, s2
	s_nop 0
	global_load_lds_dwordx4 v146, s[0:1]
	s_add_i32 m0, s2, 0x2000
	s_nop 0
	global_load_lds_dwordx4 v152, s[0:1]
	s_waitcnt vmcnt(6)
	s_barrier
; #define G_STAGE(bufoff, gbase, voff) do { _Pragma("unroll") for (int _i = 0; _i < 2; ++_i) \
;         __builtin_amdgcn_global_load_lds((const unsigned*)((const char*)(gbase) + (voff)[_i]), (LAS unsigned*)(lds + (bufoff) + ldsw + _i * 8192), 16, 0, 0); } while (0)
; #define G_LDA(dst, b, h) do { _Pragma("unroll") for (int m = 0; m < 4; ++m) _Pragma("unroll") for (int k = 0; k < 2; ++k) dst[m][k] = *(const LAS bf16x8*)(lds + G_SA(b, h) + aoff + m * 2048 + k * 1024); } while (0)
; #define G_LDB(dst, b, h) do { _Pragma("unroll") for (int n = 0; n < 2; ++n) _Pragma("unroll") for (int k = 0; k < 2; ++k) dst[n][k] = *(const LAS bf16x8*)(lds + G_SB(b, h) + boff + n * 2048 + k * 1024); } while (0)
; #define G_MMA(ai, bj, At, Bt) do { __builtin_amdgcn_s_setprio(1); _Pragma("unroll") for (int m = 0; m < 4; ++m) _Pragma("unroll") for (int n = 0; n < 2; ++n) _Pragma("unroll") for (int k = 0; k < 2; ++k) \
;         acc[ai][bj][m][n] = __builtin_amdgcn_mfma_f32_16x16x32_bf16(Bt[n][k], At[m][k], acc[ai][bj][m][n], 0, 0, 0); __builtin_amdgcn_s_setprio(0); } while (0)
; #define G_WAIT_V(n) asm volatile("s_waitcnt vmcnt(" #n ")" ::: "memory")
; #define G_WAIT_L(n) asm volatile("s_waitcnt lgkmcnt(" #n ")" ::: "memory")
; #define G_BAR __builtin_amdgcn_s_barrier()
; #define G_SCHED __builtin_amdgcn_sched_barrier(0)
; template <class J>
; DI void gemm_phase(LAS unsigned char* lds, const J& job) {
;     ...
;       G_WAIT_V(6); G_BAR; G_MMA(1, 1, At, B1); G_BAR;
;       G_LDB(B0, 1, 0); G_SCHED; G_LDA(At, 1, 0); G_STAGE(G_SA(0, 1), a2 + hstepA, voffA);
;       G_WAIT_L(8); G_BAR; G_WAIT_L(0); G_MMA(0, 0, At, B0); G_BAR; G_SCHED;
;       G_LDB(B1, 1, 1); G_STAGE(G_SB(1, 0), b3, voffB);
;       G_BAR; G_WAIT_L(0); G_MMA(0, 1, At, B1); G_BAR;
;       G_LDA(At, 1, 1); G_STAGE(G_SA(1, 0), a3, voffA);
;       G_BAR; G_WAIT_L(0); G_MMA(1, 0, At, B0); G_BAR; G_SCHED;
	v_mfma_f32_16x16x32_bf16 v[52:55], v[192:195], v[154:157], v[52:55]
	v_mfma_f32_16x16x32_bf16 v[48:51], v[200:203], v[154:157], v[48:51]
	v_mfma_f32_16x16x32_bf16 v[36:39], v[192:195], v[168:171], v[36:39]
	v_mfma_f32_16x16x32_bf16 v[32:35], v[200:203], v[168:171], v[32:35]
	v_mfma_f32_16x16x32_bf16 v[16:19], v[192:195], v[176:179], v[16:19]
	v_mfma_f32_16x16x32_bf16 v[8:11], v[200:203], v[176:179], v[8:11]
	v_mfma_f32_16x16x32_bf16 v[4:7], v[192:195], v[184:187], v[4:7]
	v_mfma_f32_16x16x32_bf16 v[0:3], v[200:203], v[184:187], v[0:3]
	v_mfma_f32_16x16x32_bf16 v[52:55], v[196:199], v[164:167], v[52:55]
	v_mfma_f32_16x16x32_bf16 v[48:51], v[204:207], v[164:167], v[48:51]
	v_mfma_f32_16x16x32_bf16 v[36:39], v[196:199], v[172:175], v[36:39]
	v_mfma_f32_16x16x32_bf16 v[32:35], v[204:207], v[172:175], v[32:35]
	v_mfma_f32_16x16x32_bf16 v[16:19], v[196:199], v[180:183], v[16:19]
	v_mfma_f32_16x16x32_bf16 v[8:11], v[204:207], v[180:183], v[8:11]
	v_mfma_f32_16x16x32_bf16 v[4:7], v[196:199], v[188:191], v[4:7]
	v_mfma_f32_16x16x32_bf16 v[0:3], v[204:207], v[188:191], v[0:3]
	s_add_i32 s2, s88, 0x100
	s_barrier
	ds_read_b128 v[128:131], v221 offset:32768
	ds_read_b128 v[132:135], v221 offset:33792
	ds_read_b128 v[136:139], v221 offset:34816
	ds_read_b128 v[140:143], v221 offset:35840
	s_add_u32 s0, s76, 0x80000
	s_addc_u32 s1, s77, 0
	ds_read_b128 v[154:157], v163 offset:32768
	ds_read_b128 v[164:167], v163 offset:33792
	ds_read_b128 v[168:171], v163 offset:34816
	ds_read_b128 v[172:175], v163 offset:35840
	ds_read_b128 v[176:179], v163 offset:36864
	ds_read_b128 v[180:183], v163 offset:37888
	ds_read_b128 v[184:187], v163 offset:38912
	ds_read_b128 v[188:191], v163 offset:39936
	s_waitcnt lgkmcnt(8)
	s_barrier
	s_waitcnt lgkmcnt(0)
	v_mfma_f32_16x16x32_bf16 v[124:127], v[128:131], v[154:157], v[124:127]
	v_mfma_f32_16x16x32_bf16 v[120:123], v[136:139], v[154:157], v[120:123]
	v_mfma_f32_16x16x32_bf16 v[108:111], v[128:131], v[168:171], v[108:111]
	v_mfma_f32_16x16x32_bf16 v[104:107], v[136:139], v[168:171], v[104:107]
	v_mfma_f32_16x16x32_bf16 v[92:95], v[128:131], v[176:179], v[92:95]
	v_mfma_f32_16x16x32_bf16 v[88:91], v[136:139], v[176:179], v[88:91]
	v_mfma_f32_16x16x32_bf16 v[76:79], v[128:131], v[184:187], v[76:79]
	v_mfma_f32_16x16x32_bf16 v[72:75], v[136:139], v[184:187], v[72:75]
	v_mfma_f32_16x16x32_bf16 v[124:127], v[132:135], v[164:167], v[124:127]
	v_mfma_f32_16x16x32_bf16 v[120:123], v[140:143], v[164:167], v[120:123]
	v_mfma_f32_16x16x32_bf16 v[108:111], v[132:135], v[172:175], v[108:111]
	v_mfma_f32_16x16x32_bf16 v[104:107], v[140:143], v[172:175], v[104:107]
	v_mfma_f32_16x16x32_bf16 v[92:95], v[132:135], v[180:183], v[92:95]
	v_mfma_f32_16x16x32_bf16 v[88:91], v[140:143], v[180:183], v[88:91]
	v_mfma_f32_16x16x32_bf16 v[76:79], v[132:135], v[188:191], v[76:79]
	v_mfma_f32_16x16x32_bf16 v[72:75], v[140:143], v[188:191], v[72:75]
	s_barrier
	s_mov_b32 m0, s37
	s_nop 0
	global_load_lds_dwordx4 v148, s[0:1]
	s_mov_b32 m0, s38
	s_nop 0
	global_load_lds_dwordx4 v150, s[0:1]
	s_add_i32 s54, s89, 0x100
	s_add_i32 s0, s2, s14
	ds_read_b128 v[192:195], v221 offset:49152
	ds_read_b128 v[196:199], v221 offset:50176
	ds_read_b128 v[200:203], v221 offset:51200
	ds_read_b128 v[204:207], v221 offset:52224
	s_mov_b32 m0, s0
	s_nop 0
	global_load_lds_dwordx4 v146, s[72:73]
	s_add_i32 m0, s0, 0x2000
	s_nop 0
	global_load_lds_dwordx4 v152, s[72:73]
	s_barrier
	s_waitcnt lgkmcnt(0)
	v_mfma_f32_16x16x32_bf16 v[116:119], v[192:195], v[154:157], v[116:119]
	v_mfma_f32_16x16x32_bf16 v[112:115], v[200:203], v[154:157], v[112:115]
	v_mfma_f32_16x16x32_bf16 v[100:103], v[192:195], v[168:171], v[100:103]
	v_mfma_f32_16x16x32_bf16 v[96:99], v[200:203], v[168:171], v[96:99]
	v_mfma_f32_16x16x32_bf16 v[84:87], v[192:195], v[176:179], v[84:87]
	v_mfma_f32_16x16x32_bf16 v[80:83], v[200:203], v[176:179], v[80:83]
	v_mfma_f32_16x16x32_bf16 v[68:71], v[192:195], v[184:187], v[68:71]
	v_mfma_f32_16x16x32_bf16 v[64:67], v[200:203], v[184:187], v[64:67]
	v_mfma_f32_16x16x32_bf16 v[116:119], v[196:199], v[164:167], v[116:119]
	v_mfma_f32_16x16x32_bf16 v[112:115], v[204:207], v[164:167], v[112:115]
	v_mfma_f32_16x16x32_bf16 v[100:103], v[196:199], v[172:175], v[100:103]
	v_mfma_f32_16x16x32_bf16 v[96:99], v[204:207], v[172:175], v[96:99]
	v_mfma_f32_16x16x32_bf16 v[84:87], v[196:199], v[180:183], v[84:87]
	v_mfma_f32_16x16x32_bf16 v[80:83], v[204:207], v[180:183], v[80:83]
	v_mfma_f32_16x16x32_bf16 v[68:71], v[196:199], v[188:191], v[68:71]
	v_mfma_f32_16x16x32_bf16 v[64:67], v[204:207], v[188:191], v[64:67]
	s_mov_b32 m0, s87
	s_barrier
	ds_read_b128 v[154:157], v163 offset:49152
	ds_read_b128 v[164:167], v163 offset:50176
	ds_read_b128 v[168:171], v163 offset:51200
	ds_read_b128 v[172:175], v163 offset:52224
	ds_read_b128 v[176:179], v163 offset:53248
	ds_read_b128 v[180:183], v163 offset:54272
	ds_read_b128 v[184:187], v163 offset:55296
	ds_read_b128 v[188:191], v163 offset:56320
	global_load_lds_dwordx4 v148, s[74:75]
	s_mov_b32 m0, s94
	s_nop 0
	global_load_lds_dwordx4 v150, s[74:75]
	s_barrier
; #define G_STAGE(bufoff, gbase, voff) do { _Pragma("unroll") for (int _i = 0; _i < 2; ++_i) \
;         __builtin_amdgcn_global_load_lds((const unsigned*)((const char*)(gbase) + (voff)[_i]), (LAS unsigned*)(lds + (bufoff) + ldsw + _i * 8192), 16, 0, 0); } while (0)
; #define G_BAR __builtin_amdgcn_s_barrier()
; template <class J>
; DI void gemm_phase(LAS unsigned char* lds, const J& job) {
;     ...
;     for (int t = 0; t < nt; t += 2) {
;       const bool last = (t == nt - 2);
;       const char* a1 = cA + G_KT(t + 1);
;       const char* a2 = last ? nA + G_KT(0) : cA + G_KT(t + 2); const char* b2 = last ? nB + G_KT(0) : cB + G_KT(t + 2);
;       const char* a3 = last ? nA + G_KT(1) : cA + G_KT(t + 3); const char* b3 = last ? nB + G_KT(1) : cB + G_KT(t + 3);
;       G_LDB(B0, 0, 0); G_SCHED; G_LDA(At, 0, 0); G_STAGE(G_SA(1, 1), a1 + hstepA, voffA);
;       G_WAIT_L(8); G_BAR; G_WAIT_L(0); G_MMA(0, 0, At, B0); G_BAR; G_SCHED;
;       G_LDB(B1, 0, 1); G_STAGE(G_SB(0, 0), b2, voffB);
;       G_BAR; G_WAIT_L(0); G_MMA(0, 1, At, B1); G_BAR;
;       G_LDA(At, 0, 1); G_STAGE(G_SA(0, 0), a2, voffA);
;       G_BAR; G_WAIT_L(0); G_MMA(1, 0, At, B0); G_BAR; G_SCHED;
;       G_STAGE(G_SB(0, 1), b2 + hstepB, voffB);
;       G_WAIT_V(6); G_BAR; G_MMA(1, 1, At, B1); G_BAR;
;       G_LDB(B0, 1, 0); G_SCHED; G_LDA(At, 1, 0); G_STAGE(G_SA(0, 1), a2 + hstepA, voffA);
;       G_WAIT_L(8); G_BAR; G_WAIT_L(0); G_MMA(0, 0, At, B0); G_BAR; G_SCHED;
;       G_LDB(B1, 1, 1); G_STAGE(G_SB(1, 0), b3, voffB);
;       G_BAR; G_WAIT_L(0); G_MMA(0, 1, At, B1); G_BAR;
;       G_LDA(At, 1, 1); G_STAGE(G_SA(1, 0), a3, voffA);
;       G_BAR; G_WAIT_L(0); G_MMA(1, 0, At, B0); G_BAR; G_SCHED;
;       G_STAGE(G_SB(1, 1), b3 + hstepB, voffB);
;       G_WAIT_V(6); G_BAR; G_MMA(1, 1, At, B1); G_BAR;
;   DI void epi(const Acc& acc, const Unit& u, int wr, int wc, int fr, int fq) const {
;     ...
;     for (int ai = 0; ai < 2; ++ai) {
;       f32x4 res[4][2][2];
; #pragma unroll
;       for (int m = 0; m < 4; ++m) {
;         const int row = u.pm * 256 + ai * HALF + wr * 64 + m * 16 + fr;
;         const float* src = (l == 0) ? xp + (size_t)row * DM : out + (size_t)row * DM;
; #pragma unroll
;         for (int bj = 0; bj < 2; ++bj) { const int col = u.pn * 256 + bj * HALF + wc * 32 + 8 * fq; res[m][bj][0] = *(const f32x4*)(src + col); res[m][bj][1] = *(const f32x4*)(src + col + 4); }
;       }
	s_waitcnt lgkmcnt(0)
	v_mfma_f32_16x16x32_bf16 v[60:63], v[128:131], v[154:157], v[60:63]
	v_mfma_f32_16x16x32_bf16 v[56:59], v[136:139], v[154:157], v[56:59]
	v_mfma_f32_16x16x32_bf16 v[44:47], v[128:131], v[168:171], v[44:47]
	v_mfma_f32_16x16x32_bf16 v[40:43], v[136:139], v[168:171], v[40:43]
	v_mfma_f32_16x16x32_bf16 v[28:31], v[128:131], v[176:179], v[28:31]
	v_mfma_f32_16x16x32_bf16 v[24:27], v[136:139], v[176:179], v[24:27]
	v_mfma_f32_16x16x32_bf16 v[20:23], v[128:131], v[184:187], v[20:23]
	v_mfma_f32_16x16x32_bf16 v[12:15], v[136:139], v[184:187], v[12:15]
	v_mfma_f32_16x16x32_bf16 v[60:63], v[132:135], v[164:167], v[60:63]
	v_mfma_f32_16x16x32_bf16 v[56:59], v[140:143], v[164:167], v[56:59]
	v_mfma_f32_16x16x32_bf16 v[44:47], v[132:135], v[172:175], v[44:47]
	v_mfma_f32_16x16x32_bf16 v[40:43], v[140:143], v[172:175], v[40:43]
	v_mfma_f32_16x16x32_bf16 v[28:31], v[132:135], v[180:183], v[28:31]
	v_mfma_f32_16x16x32_bf16 v[24:27], v[140:143], v[180:183], v[24:27]
	v_mfma_f32_16x16x32_bf16 v[20:23], v[132:135], v[188:191], v[20:23]
	v_mfma_f32_16x16x32_bf16 v[12:15], v[140:143], v[188:191], v[12:15]
	s_barrier
	s_add_u32 s0, s72, 0x80000
	s_addc_u32 s1, s73, 0
	s_add_i32 s2, s54, s14
	s_mov_b32 m0, s2
	s_nop 0
	global_load_lds_dwordx4 v146, s[0:1]
	s_add_i32 m0, s2, 0x2000
	s_nop 0
	global_load_lds_dwordx4 v152, s[0:1]
	s_add_i32 s7, s7, 2
	s_addk_i32 s57, 0x100
	s_addk_i32 s44, 0x100
	s_add_i32 s1, s57, 0xffffff80
	s_and_b32 s0, s44, 0xf80
	s_and_b32 s1, s1, 0xf00
	s_add_u32 s2, s70, s1
	s_addc_u32 s72, s71, 0
	s_add_u32 s1, s68, s1
	s_addc_u32 s73, s69, 0
	s_and_b32 s74, s57, 0xf80
	s_add_u32 s80, s70, s74
	s_addc_u32 s75, s71, 0
	s_add_u32 s54, s68, s74
	s_addc_u32 s55, s69, 0
	s_cmp_eq_u32 s7, 28
	s_cselect_b32 s77, vcc_lo, s72
	s_cselect_b32 s76, s47, s2
	s_cselect_b32 s79, s33, s73
	s_cselect_b32 s78, vcc_hi, s1
	s_cselect_b32 s75, s4, s75
	s_cselect_b32 s74, s97, s80
	s_cselect_b32 s73, s6, s55
	s_cselect_b32 s72, s5, s54
	s_waitcnt vmcnt(6)
	s_barrier
	v_mfma_f32_16x16x32_bf16 v[52:55], v[192:195], v[154:157], v[52:55]
	v_mfma_f32_16x16x32_bf16 v[48:51], v[200:203], v[154:157], v[48:51]
	v_mfma_f32_16x16x32_bf16 v[36:39], v[192:195], v[168:171], v[36:39]
	v_mfma_f32_16x16x32_bf16 v[32:35], v[200:203], v[168:171], v[32:35]
	v_mfma_f32_16x16x32_bf16 v[16:19], v[192:195], v[176:179], v[16:19]
	v_mfma_f32_16x16x32_bf16 v[8:11], v[200:203], v[176:179], v[8:11]
	v_mfma_f32_16x16x32_bf16 v[4:7], v[192:195], v[184:187], v[4:7]
	v_mfma_f32_16x16x32_bf16 v[0:3], v[200:203], v[184:187], v[0:3]
	v_mfma_f32_16x16x32_bf16 v[52:55], v[196:199], v[164:167], v[52:55]
	v_mfma_f32_16x16x32_bf16 v[48:51], v[204:207], v[164:167], v[48:51]
	v_mfma_f32_16x16x32_bf16 v[36:39], v[196:199], v[172:175], v[36:39]
	v_mfma_f32_16x16x32_bf16 v[32:35], v[204:207], v[172:175], v[32:35]
	v_mfma_f32_16x16x32_bf16 v[16:19], v[196:199], v[180:183], v[16:19]
	v_mfma_f32_16x16x32_bf16 v[8:11], v[204:207], v[180:183], v[8:11]
	v_mfma_f32_16x16x32_bf16 v[4:7], v[196:199], v[188:191], v[4:7]
	v_mfma_f32_16x16x32_bf16 v[0:3], v[204:207], v[188:191], v[0:3]
	s_cmp_gt_u32 s7, 29
	s_barrier
	s_cbranch_scc0 .LBB0_42
	s_lshl_b32 s0, s66, 8
	v_mov_b32_e32 v128, v161
	v_mov_b32_e32 v129, v160
	s_add_i32 s0, s0, s67
	s_and_b64 vcc, exec, s[18:19]
	v_add_u32_e32 v156, s0, v129
	s_lshl_b32 s0, s46, 8
	s_or_b32 s0, s0, s83
	v_lshl_add_u32 v128, v128, 3, s0
	v_ashrrev_i32_e32 v157, 31, v156
	v_ashrrev_i32_e32 v129, 31, v128
	v_lshlrev_b64 v[212:213], 13, v[156:157]
	v_lshl_add_u64 v[130:131], s[8:9], 0, v[212:213]
	v_lshlrev_b64 v[154:155], 2, v[128:129]
	v_lshl_add_u64 v[128:129], v[130:131], 0, v[154:155]
	global_load_dwordx4 v[164:167], v[128:129], off offset:16
	global_load_dwordx4 v[168:171], v[128:129], off
	global_load_dwordx4 v[172:175], v[128:129], off offset:528
	global_load_dwordx4 v[176:179], v[128:129], off offset:512
	v_add_u32_e32 v128, 16, v156
	v_ashrrev_i32_e32 v129, 31, v128
	v_lshlrev_b64 v[214:215], 13, v[128:129]
	v_lshl_add_u64 v[128:129], s[8:9], 0, v[214:215]
	v_lshl_add_u64 v[128:129], v[128:129], 0, v[154:155]
	global_load_dwordx4 v[180:183], v[128:129], off offset:16
	global_load_dwordx4 v[184:187], v[128:129], off
	global_load_dwordx4 v[188:191], v[128:129], off offset:528
	global_load_dwordx4 v[192:195], v[128:129], off offset:512
	v_add_u32_e32 v128, 32, v156
	v_ashrrev_i32_e32 v129, 31, v128
	v_lshlrev_b64 v[216:217], 13, v[128:129]
	v_lshl_add_u64 v[128:129], s[8:9], 0, v[216:217]
	v_lshl_add_u64 v[128:129], v[128:129], 0, v[154:155]
	global_load_dwordx4 v[196:199], v[128:129], off offset:16
	global_load_dwordx4 v[200:203], v[128:129], off
	global_load_dwordx4 v[204:207], v[128:129], off offset:528
	global_load_dwordx4 v[208:211], v[128:129], off offset:512
	v_add_u32_e32 v128, 48, v156
	v_ashrrev_i32_e32 v129, 31, v128
	v_lshlrev_b64 v[158:159], 13, v[128:129]
	v_lshl_add_u64 v[128:129], s[8:9], 0, v[158:159]
	v_lshl_add_u64 v[136:137], v[128:129], 0, v[154:155]
	global_load_dwordx4 v[132:135], v[136:137], off offset:16
	global_load_dwordx4 v[140:143], v[136:137], off
	global_load_dwordx4 v[128:131], v[136:137], off offset:528
	s_nop 0
	global_load_dwordx4 v[136:139], v[136:137], off offset:512
	v_lshl_add_u64 v[212:213], s[16:17], 0, v[212:213]
	s_mov_b32 s46, s22
	s_mov_b32 s66, s20
	s_mov_b64 s[68:69], s[64:65]
	s_mov_b64 s[70:71], s[62:63]
	s_movk_i32 s54, 0x4000
	s_movk_i32 s55, 0x6000
	v_readlane_b32 s0, v255, 23
	s_cmpk_gt_u32 s0, 0xff
	s_cbranch_scc1 .Lds_out_x
	s_barrier

; #define G_STAGE(bufoff, gbase, voff) do { _Pragma("unroll") for (int _i = 0; _i < 2; ++_i) \
;         __builtin_amdgcn_global_load_lds((const unsigned*)((const char*)(gbase) + (voff)[_i]), (LAS unsigned*)(lds + (bufoff) + ldsw + _i * 8192), 16, 0, 0); } while (0)
; #define G_LDA(dst, b, h) do { _Pragma("unroll") for (int m = 0; m < 4; ++m) _Pragma("unroll") for (int k = 0; k < 2; ++k) dst[m][k] = *(const LAS bf16x8*)(lds + G_SA(b, h) + aoff + m * 2048 + k * 1024); } while (0)
; #define G_LDB(dst, b, h) do { _Pragma("unroll") for (int n = 0; n < 2; ++n) _Pragma("unroll") for (int k = 0; k < 2; ++k) dst[n][k] = *(const LAS bf16x8*)(lds + G_SB(b, h) + boff + n * 2048 + k * 1024); } while (0)
; #define G_MMA(ai, bj, At, Bt) do { __builtin_amdgcn_s_setprio(1); _Pragma("unroll") for (int m = 0; m < 4; ++m) _Pragma("unroll") for (int n = 0; n < 2; ++n) _Pragma("unroll") for (int k = 0; k < 2; ++k) \
;         acc[ai][bj][m][n] = __builtin_amdgcn_mfma_f32_16x16x32_bf16(Bt[n][k], At[m][k], acc[ai][bj][m][n], 0, 0, 0); __builtin_amdgcn_s_setprio(0); } while (0)
; #define G_WAIT_V(n) asm volatile("s_waitcnt vmcnt(" #n ")" ::: "memory")
; #define G_WAIT_L(n) asm volatile("s_waitcnt lgkmcnt(" #n ")" ::: "memory")
; #define G_BAR __builtin_amdgcn_s_barrier()
; #define G_SCHED __builtin_amdgcn_sched_barrier(0)
; template <class J>
; DI void gemm_phase(LAS unsigned char* lds, const J& job) {
;     ...
;       G_LDB(B0, 0, 0); G_SCHED; G_LDA(At, 0, 0); G_STAGE(G_SA(1, 1), a1 + hstepA, voffA);
;       G_WAIT_L(8); G_BAR; G_WAIT_L(0); G_MMA(0, 0, At, B0); G_BAR; G_SCHED;
;       G_LDB(B1, 0, 1); G_STAGE(G_SB(0, 0), b2, voffB);
;       G_BAR; G_WAIT_L(0); G_MMA(0, 1, At, B1); G_BAR;
;       G_LDA(At, 0, 1); G_STAGE(G_SA(0, 0), a2, voffA);
;       G_BAR; G_WAIT_L(0); G_MMA(1, 0, At, B0); G_BAR; G_SCHED;
;       G_STAGE(G_SB(0, 1), b2 + hstepB, voffB);
;       G_WAIT_V(6); G_BAR; G_MMA(1, 1, At, B1); G_BAR;
.LBB0_74:
	s_add_i32 s2, s84, 0x100
	ds_read_b128 v[84:87], v204
	ds_read_b128 v[88:91], v204 offset:1024
	ds_read_b128 v[96:99], v204 offset:2048
	ds_read_b128 v[100:103], v204 offset:3072
	s_add_u32 s0, s19, s0
	s_addc_u32 s1, s21, 0
	ds_read_b128 v[154:157], v249
	ds_read_b128 v[158:161], v249 offset:1024
	ds_read_b128 v[162:165], v249 offset:2048
	ds_read_b128 v[166:169], v249 offset:3072
	ds_read_b128 v[170:173], v249 offset:4096
	ds_read_b128 v[174:177], v249 offset:5120
	ds_read_b128 v[178:181], v249 offset:6144
	ds_read_b128 v[182:185], v249 offset:7168
	s_waitcnt lgkmcnt(8)
	s_barrier
	s_waitcnt lgkmcnt(0)
	v_mfma_f32_16x16x32_bf16 v[140:143], v[84:87], v[154:157], v[140:143]
	v_mfma_f32_16x16x32_bf16 v[136:139], v[96:99], v[154:157], v[136:139]
	v_mfma_f32_16x16x32_bf16 v[124:127], v[84:87], v[162:165], v[124:127]
	v_mfma_f32_16x16x32_bf16 v[120:123], v[96:99], v[162:165], v[120:123]
	v_mfma_f32_16x16x32_bf16 v[108:111], v[84:87], v[170:173], v[108:111]
	v_mfma_f32_16x16x32_bf16 v[104:107], v[96:99], v[170:173], v[104:107]
	v_mfma_f32_16x16x32_bf16 v[76:79], v[84:87], v[178:181], v[76:79]
	v_mfma_f32_16x16x32_bf16 v[72:75], v[96:99], v[178:181], v[72:75]
	v_mfma_f32_16x16x32_bf16 v[140:143], v[88:91], v[158:161], v[140:143]
	v_mfma_f32_16x16x32_bf16 v[136:139], v[100:103], v[158:161], v[136:139]
	v_mfma_f32_16x16x32_bf16 v[124:127], v[88:91], v[166:169], v[124:127]
	v_mfma_f32_16x16x32_bf16 v[120:123], v[100:103], v[166:169], v[120:123]
	v_mfma_f32_16x16x32_bf16 v[108:111], v[88:91], v[174:177], v[108:111]
	v_mfma_f32_16x16x32_bf16 v[104:107], v[100:103], v[174:177], v[104:107]
	v_mfma_f32_16x16x32_bf16 v[76:79], v[88:91], v[182:185], v[76:79]
	v_mfma_f32_16x16x32_bf16 v[72:75], v[100:103], v[182:185], v[72:75]
	s_barrier
	s_add_i32 m0, s14, 0xc000
	s_nop 0
	global_load_lds_dwordx4 v148, s[0:1]
	s_add_i32 m0, s14, 0xe000
	s_nop 0
	global_load_lds_dwordx4 v150, s[0:1]
	s_add_i32 s38, s85, 0x100
	s_add_i32 s0, s2, s78
	s_mov_b32 m0, s0
	ds_read_b128 v[186:189], v204 offset:16384
	ds_read_b128 v[190:193], v204 offset:17408
	ds_read_b128 v[194:197], v204 offset:18432
	ds_read_b128 v[198:201], v204 offset:19456
	global_load_lds_dwordx4 v146, s[76:77]
	s_add_i32 m0, s0, 0x2000
	s_nop 0
	global_load_lds_dwordx4 v152, s[76:77]
	s_barrier
	s_waitcnt lgkmcnt(0)
	v_mfma_f32_16x16x32_bf16 v[132:135], v[186:189], v[154:157], v[132:135]
	v_mfma_f32_16x16x32_bf16 v[128:131], v[194:197], v[154:157], v[128:131]
	v_mfma_f32_16x16x32_bf16 v[116:119], v[186:189], v[162:165], v[116:119]
	v_mfma_f32_16x16x32_bf16 v[112:115], v[194:197], v[162:165], v[112:115]
	v_mfma_f32_16x16x32_bf16 v[92:95], v[186:189], v[170:173], v[92:95]
	v_mfma_f32_16x16x32_bf16 v[80:83], v[194:197], v[170:173], v[80:83]
	v_mfma_f32_16x16x32_bf16 v[68:71], v[186:189], v[178:181], v[68:71]
	v_mfma_f32_16x16x32_bf16 v[64:67], v[194:197], v[178:181], v[64:67]
	v_mfma_f32_16x16x32_bf16 v[132:135], v[190:193], v[158:161], v[132:135]
	v_mfma_f32_16x16x32_bf16 v[128:131], v[198:201], v[158:161], v[128:131]
	v_mfma_f32_16x16x32_bf16 v[116:119], v[190:193], v[166:169], v[116:119]
	v_mfma_f32_16x16x32_bf16 v[112:115], v[198:201], v[166:169], v[112:115]
	v_mfma_f32_16x16x32_bf16 v[92:95], v[190:193], v[174:177], v[92:95]
	v_mfma_f32_16x16x32_bf16 v[80:83], v[198:201], v[174:177], v[80:83]
	v_mfma_f32_16x16x32_bf16 v[68:71], v[190:193], v[182:185], v[68:71]
	v_mfma_f32_16x16x32_bf16 v[64:67], v[198:201], v[182:185], v[64:67]
	s_mov_b32 m0, s14
	s_barrier
	ds_read_b128 v[154:157], v249 offset:16384
	ds_read_b128 v[158:161], v249 offset:17408
	ds_read_b128 v[162:165], v249 offset:18432
	ds_read_b128 v[166:169], v249 offset:19456
	ds_read_b128 v[170:173], v249 offset:20480
	ds_read_b128 v[174:177], v249 offset:21504
	ds_read_b128 v[178:181], v249 offset:22528
	ds_read_b128 v[182:185], v249 offset:23552
	global_load_lds_dwordx4 v148, s[74:75]
	s_mov_b32 m0, s15
	s_nop 0
	global_load_lds_dwordx4 v150, s[74:75]
	s_barrier
	s_waitcnt lgkmcnt(0)
	v_mfma_f32_16x16x32_bf16 v[60:63], v[84:87], v[154:157], v[60:63]
	v_mfma_f32_16x16x32_bf16 v[56:59], v[96:99], v[154:157], v[56:59]
	v_mfma_f32_16x16x32_bf16 v[44:47], v[84:87], v[162:165], v[44:47]
	v_mfma_f32_16x16x32_bf16 v[40:43], v[96:99], v[162:165], v[40:43]
	v_mfma_f32_16x16x32_bf16 v[28:31], v[84:87], v[170:173], v[28:31]
	v_mfma_f32_16x16x32_bf16 v[24:27], v[96:99], v[170:173], v[24:27]
	v_mfma_f32_16x16x32_bf16 v[12:15], v[84:87], v[178:181], v[12:15]
	v_mfma_f32_16x16x32_bf16 v[8:11], v[96:99], v[178:181], v[8:11]
	v_mfma_f32_16x16x32_bf16 v[60:63], v[88:91], v[158:161], v[60:63]
	v_mfma_f32_16x16x32_bf16 v[56:59], v[100:103], v[158:161], v[56:59]
	v_mfma_f32_16x16x32_bf16 v[44:47], v[88:91], v[166:169], v[44:47]
	v_mfma_f32_16x16x32_bf16 v[40:43], v[100:103], v[166:169], v[40:43]
	v_mfma_f32_16x16x32_bf16 v[28:31], v[88:91], v[174:177], v[28:31]
	v_mfma_f32_16x16x32_bf16 v[24:27], v[100:103], v[174:177], v[24:27]
	v_mfma_f32_16x16x32_bf16 v[12:15], v[88:91], v[182:185], v[12:15]
	v_mfma_f32_16x16x32_bf16 v[8:11], v[100:103], v[182:185], v[8:11]
	s_barrier
	s_add_u32 s0, s76, 0x1000000
	s_addc_u32 s1, s77, 0
	s_add_i32 s2, s38, s78
	s_mov_b32 m0, s2
	s_nop 0
	global_load_lds_dwordx4 v146, s[0:1]
	s_add_i32 m0, s2, 0x2000
	s_nop 0
	global_load_lds_dwordx4 v152, s[0:1]
	s_waitcnt vmcnt(6)
	s_barrier
; #define G_STAGE(bufoff, gbase, voff) do { _Pragma("unroll") for (int _i = 0; _i < 2; ++_i) \
;         __builtin_amdgcn_global_load_lds((const unsigned*)((const char*)(gbase) + (voff)[_i]), (LAS unsigned*)(lds + (bufoff) + ldsw + _i * 8192), 16, 0, 0); } while (0)
; #define G_LDA(dst, b, h) do { _Pragma("unroll") for (int m = 0; m < 4; ++m) _Pragma("unroll") for (int k = 0; k < 2; ++k) dst[m][k] = *(const LAS bf16x8*)(lds + G_SA(b, h) + aoff + m * 2048 + k * 1024); } while (0)
; #define G_LDB(dst, b, h) do { _Pragma("unroll") for (int n = 0; n < 2; ++n) _Pragma("unroll") for (int k = 0; k < 2; ++k) dst[n][k] = *(const LAS bf16x8*)(lds + G_SB(b, h) + boff + n * 2048 + k * 1024); } while (0)
; #define G_MMA(ai, bj, At, Bt) do { __builtin_amdgcn_s_setprio(1); _Pragma("unroll") for (int m = 0; m < 4; ++m) _Pragma("unroll") for (int n = 0; n < 2; ++n) _Pragma("unroll") for (int k = 0; k < 2; ++k) \
;         acc[ai][bj][m][n] = __builtin_amdgcn_mfma_f32_16x16x32_bf16(Bt[n][k], At[m][k], acc[ai][bj][m][n], 0, 0, 0); __builtin_amdgcn_s_setprio(0); } while (0)
; #define G_WAIT_V(n) asm volatile("s_waitcnt vmcnt(" #n ")" ::: "memory")
; #define G_WAIT_L(n) asm volatile("s_waitcnt lgkmcnt(" #n ")" ::: "memory")
; #define G_BAR __builtin_amdgcn_s_barrier()
; #define G_SCHED __builtin_amdgcn_sched_barrier(0)
; template <class J>
; DI void gemm_phase(LAS unsigned char* lds, const J& job) {
;     ...
;       G_WAIT_V(6); G_BAR; G_MMA(1, 1, At, B1); G_BAR;
;       G_LDB(B0, 1, 0); G_SCHED; G_LDA(At, 1, 0); G_STAGE(G_SA(0, 1), a2 + hstepA, voffA);
;       G_WAIT_L(8); G_BAR; G_WAIT_L(0); G_MMA(0, 0, At, B0); G_BAR; G_SCHED;
;       G_LDB(B1, 1, 1); G_STAGE(G_SB(1, 0), b3, voffB);
;       G_BAR; G_WAIT_L(0); G_MMA(0, 1, At, B1); G_BAR;
;       G_LDA(At, 1, 1); G_STAGE(G_SA(1, 0), a3, voffA);
;       G_BAR; G_WAIT_L(0); G_MMA(1, 0, At, B0); G_BAR; G_SCHED;
	v_mfma_f32_16x16x32_bf16 v[52:55], v[186:189], v[154:157], v[52:55]
	v_mfma_f32_16x16x32_bf16 v[48:51], v[194:197], v[154:157], v[48:51]
	v_mfma_f32_16x16x32_bf16 v[36:39], v[186:189], v[162:165], v[36:39]
	v_mfma_f32_16x16x32_bf16 v[32:35], v[194:197], v[162:165], v[32:35]
	v_mfma_f32_16x16x32_bf16 v[20:23], v[186:189], v[170:173], v[20:23]
	v_mfma_f32_16x16x32_bf16 v[16:19], v[194:197], v[170:173], v[16:19]
	v_mfma_f32_16x16x32_bf16 v[4:7], v[186:189], v[178:181], v[4:7]
	v_mfma_f32_16x16x32_bf16 v[0:3], v[194:197], v[178:181], v[0:3]
	v_mfma_f32_16x16x32_bf16 v[52:55], v[190:193], v[158:161], v[52:55]
	v_mfma_f32_16x16x32_bf16 v[48:51], v[198:201], v[158:161], v[48:51]
	v_mfma_f32_16x16x32_bf16 v[36:39], v[190:193], v[166:169], v[36:39]
	v_mfma_f32_16x16x32_bf16 v[32:35], v[198:201], v[166:169], v[32:35]
	v_mfma_f32_16x16x32_bf16 v[20:23], v[190:193], v[174:177], v[20:23]
	v_mfma_f32_16x16x32_bf16 v[16:19], v[198:201], v[174:177], v[16:19]
	v_mfma_f32_16x16x32_bf16 v[4:7], v[190:193], v[182:185], v[4:7]
	v_mfma_f32_16x16x32_bf16 v[0:3], v[198:201], v[182:185], v[0:3]
	s_add_i32 s2, s88, 0x100
	s_barrier
	ds_read_b128 v[84:87], v204 offset:32768
	ds_read_b128 v[88:91], v204 offset:33792
	ds_read_b128 v[96:99], v204 offset:34816
	ds_read_b128 v[100:103], v204 offset:35840
	s_add_u32 s0, s74, 0x80000
	s_addc_u32 s1, s75, 0
	ds_read_b128 v[154:157], v249 offset:32768
	ds_read_b128 v[158:161], v249 offset:33792
	ds_read_b128 v[162:165], v249 offset:34816
	ds_read_b128 v[166:169], v249 offset:35840
	ds_read_b128 v[170:173], v249 offset:36864
	ds_read_b128 v[174:177], v249 offset:37888
	ds_read_b128 v[178:181], v249 offset:38912
	ds_read_b128 v[182:185], v249 offset:39936
	s_waitcnt lgkmcnt(8)
	s_barrier
	s_waitcnt lgkmcnt(0)
	v_mfma_f32_16x16x32_bf16 v[140:143], v[84:87], v[154:157], v[140:143]
	v_mfma_f32_16x16x32_bf16 v[136:139], v[96:99], v[154:157], v[136:139]
	v_mfma_f32_16x16x32_bf16 v[124:127], v[84:87], v[162:165], v[124:127]
	v_mfma_f32_16x16x32_bf16 v[120:123], v[96:99], v[162:165], v[120:123]
	v_mfma_f32_16x16x32_bf16 v[108:111], v[84:87], v[170:173], v[108:111]
	v_mfma_f32_16x16x32_bf16 v[104:107], v[96:99], v[170:173], v[104:107]
	v_mfma_f32_16x16x32_bf16 v[76:79], v[84:87], v[178:181], v[76:79]
	v_mfma_f32_16x16x32_bf16 v[72:75], v[96:99], v[178:181], v[72:75]
	v_mfma_f32_16x16x32_bf16 v[140:143], v[88:91], v[158:161], v[140:143]
	v_mfma_f32_16x16x32_bf16 v[136:139], v[100:103], v[158:161], v[136:139]
	v_mfma_f32_16x16x32_bf16 v[124:127], v[88:91], v[166:169], v[124:127]
	v_mfma_f32_16x16x32_bf16 v[120:123], v[100:103], v[166:169], v[120:123]
	v_mfma_f32_16x16x32_bf16 v[108:111], v[88:91], v[174:177], v[108:111]
	v_mfma_f32_16x16x32_bf16 v[104:107], v[100:103], v[174:177], v[104:107]
	v_mfma_f32_16x16x32_bf16 v[76:79], v[88:91], v[182:185], v[76:79]
	v_mfma_f32_16x16x32_bf16 v[72:75], v[100:103], v[182:185], v[72:75]
	s_barrier
	s_mov_b32 m0, s83
	s_nop 0
	global_load_lds_dwordx4 v148, s[0:1]
	s_mov_b32 m0, s36
	s_nop 0
	global_load_lds_dwordx4 v150, s[0:1]
	s_add_i32 s38, s89, 0x100
	s_add_i32 s0, s2, s78
	s_mov_b32 m0, s0
	ds_read_b128 v[186:189], v204 offset:49152
	ds_read_b128 v[190:193], v204 offset:50176
	ds_read_b128 v[194:197], v204 offset:51200
	ds_read_b128 v[198:201], v204 offset:52224
	global_load_lds_dwordx4 v146, s[70:71]
	s_add_i32 m0, s0, 0x2000
	s_nop 0
	global_load_lds_dwordx4 v152, s[70:71]
	s_barrier
	s_waitcnt lgkmcnt(0)
	v_mfma_f32_16x16x32_bf16 v[132:135], v[186:189], v[154:157], v[132:135]
	v_mfma_f32_16x16x32_bf16 v[128:131], v[194:197], v[154:157], v[128:131]
	v_mfma_f32_16x16x32_bf16 v[116:119], v[186:189], v[162:165], v[116:119]
	v_mfma_f32_16x16x32_bf16 v[112:115], v[194:197], v[162:165], v[112:115]
	v_mfma_f32_16x16x32_bf16 v[92:95], v[186:189], v[170:173], v[92:95]
	v_mfma_f32_16x16x32_bf16 v[80:83], v[194:197], v[170:173], v[80:83]
	v_mfma_f32_16x16x32_bf16 v[68:71], v[186:189], v[178:181], v[68:71]
	v_mfma_f32_16x16x32_bf16 v[64:67], v[194:197], v[178:181], v[64:67]
	v_mfma_f32_16x16x32_bf16 v[132:135], v[190:193], v[158:161], v[132:135]
	v_mfma_f32_16x16x32_bf16 v[128:131], v[198:201], v[158:161], v[128:131]
	v_mfma_f32_16x16x32_bf16 v[116:119], v[190:193], v[166:169], v[116:119]
	v_mfma_f32_16x16x32_bf16 v[112:115], v[198:201], v[166:169], v[112:115]
	v_mfma_f32_16x16x32_bf16 v[92:95], v[190:193], v[174:177], v[92:95]
	v_mfma_f32_16x16x32_bf16 v[80:83], v[198:201], v[174:177], v[80:83]
	v_mfma_f32_16x16x32_bf16 v[68:71], v[190:193], v[182:185], v[68:71]
	v_mfma_f32_16x16x32_bf16 v[64:67], v[198:201], v[182:185], v[64:67]
	s_mov_b32 m0, s24
	s_barrier
	ds_read_b128 v[154:157], v249 offset:49152
	ds_read_b128 v[158:161], v249 offset:50176
	ds_read_b128 v[162:165], v249 offset:51200
	ds_read_b128 v[166:169], v249 offset:52224
	ds_read_b128 v[170:173], v249 offset:53248
	ds_read_b128 v[174:177], v249 offset:54272
	ds_read_b128 v[178:181], v249 offset:55296
	ds_read_b128 v[182:185], v249 offset:56320
	global_load_lds_dwordx4 v148, s[72:73]
	s_mov_b32 m0, s25
	s_nop 0
	global_load_lds_dwordx4 v150, s[72:73]
	s_barrier
	s_waitcnt lgkmcnt(0)
	v_mfma_f32_16x16x32_bf16 v[60:63], v[84:87], v[154:157], v[60:63]
	v_mfma_f32_16x16x32_bf16 v[56:59], v[96:99], v[154:157], v[56:59]
	v_mfma_f32_16x16x32_bf16 v[44:47], v[84:87], v[162:165], v[44:47]
	v_mfma_f32_16x16x32_bf16 v[40:43], v[96:99], v[162:165], v[40:43]
	v_mfma_f32_16x16x32_bf16 v[28:31], v[84:87], v[170:173], v[28:31]
	v_mfma_f32_16x16x32_bf16 v[24:27], v[96:99], v[170:173], v[24:27]
	v_mfma_f32_16x16x32_bf16 v[12:15], v[84:87], v[178:181], v[12:15]
	v_mfma_f32_16x16x32_bf16 v[8:11], v[96:99], v[178:181], v[8:11]
	v_mfma_f32_16x16x32_bf16 v[60:63], v[88:91], v[158:161], v[60:63]
	v_mfma_f32_16x16x32_bf16 v[56:59], v[100:103], v[158:161], v[56:59]
	v_mfma_f32_16x16x32_bf16 v[44:47], v[88:91], v[166:169], v[44:47]
	v_mfma_f32_16x16x32_bf16 v[40:43], v[100:103], v[166:169], v[40:43]
	v_mfma_f32_16x16x32_bf16 v[28:31], v[88:91], v[174:177], v[28:31]
	v_mfma_f32_16x16x32_bf16 v[24:27], v[100:103], v[174:177], v[24:27]
	v_mfma_f32_16x16x32_bf16 v[12:15], v[88:91], v[182:185], v[12:15]
	v_mfma_f32_16x16x32_bf16 v[8:11], v[100:103], v[182:185], v[8:11]
	s_barrier
; #define G_STAGE(bufoff, gbase, voff) do { _Pragma("unroll") for (int _i = 0; _i < 2; ++_i) \
;         __builtin_amdgcn_global_load_lds((const unsigned*)((const char*)(gbase) + (voff)[_i]), (LAS unsigned*)(lds + (bufoff) + ldsw + _i * 8192), 16, 0, 0); } while (0)
; #define G_MMA(ai, bj, At, Bt) do { __builtin_amdgcn_s_setprio(1); _Pragma("unroll") for (int m = 0; m < 4; ++m) _Pragma("unroll") for (int n = 0; n < 2; ++n) _Pragma("unroll") for (int k = 0; k < 2; ++k) \
;         acc[ai][bj][m][n] = __builtin_amdgcn_mfma_f32_16x16x32_bf16(Bt[n][k], At[m][k], acc[ai][bj][m][n], 0, 0, 0); __builtin_amdgcn_s_setprio(0); } while (0)
; #define G_WAIT_V(n) asm volatile("s_waitcnt vmcnt(" #n ")" ::: "memory")
; #define G_BAR __builtin_amdgcn_s_barrier()
; template <class J>
; DI void gemm_phase(LAS unsigned char* lds, const J& job) {
;     ...
;     for (int t = 0; t < nt; t += 2) {
;       const bool last = (t == nt - 2);
;       const char* a1 = cA + G_KT(t + 1);
;       const char* a2 = last ? nA + G_KT(0) : cA + G_KT(t + 2); const char* b2 = last ? nB + G_KT(0) : cB + G_KT(t + 2);
;       const char* a3 = last ? nA + G_KT(1) : cA + G_KT(t + 3); const char* b3 = last ? nB + G_KT(1) : cB + G_KT(t + 3);
;     ...
;       G_STAGE(G_SB(1, 1), b3 + hstepB, voffB);
;       G_WAIT_V(6); G_BAR; G_MMA(1, 1, At, B1); G_BAR;
	s_add_u32 s0, s70, 0x1000000
	s_addc_u32 s1, s71, 0
	s_add_i32 s2, s38, s78
	s_mov_b32 m0, s2
	s_nop 0
	global_load_lds_dwordx4 v146, s[0:1]
	s_add_i32 m0, s2, 0x2000
	s_nop 0
	global_load_lds_dwordx4 v152, s[0:1]
	s_add_i32 s6, s6, 2
	s_addk_i32 s56, 0x100
	s_addk_i32 s7, 0x100
	s_add_i32 s1, s56, 0xffffff80
	s_and_b32 s0, s7, 0xf80
	s_and_b32 s1, s1, 0xf00
	s_add_u32 s57, s68, s1
	s_addc_u32 s70, s69, 0
	s_add_u32 s1, s66, s1
	s_addc_u32 s71, s67, 0
	s_and_b32 s72, s56, 0xf80
	s_add_u32 s80, s68, s72
	s_addc_u32 s73, s69, 0
	s_add_u32 s38, s66, s72
	s_addc_u32 s2, s67, 0
	s_cmp_eq_u32 s6, 28
	s_cselect_b32 s75, s46, s70
	s_cselect_b32 s74, s45, s57
	s_cselect_b32 s77, vcc_lo, s71
	s_cselect_b32 s76, s47, s1
	s_cselect_b32 s73, s97, s73
	s_cselect_b32 s72, s33, s80
	s_cselect_b32 s71, s5, s2
	s_cselect_b32 s70, vcc_hi, s38
	s_waitcnt vmcnt(6)
	s_barrier
	v_mfma_f32_16x16x32_bf16 v[52:55], v[186:189], v[154:157], v[52:55]
	v_mfma_f32_16x16x32_bf16 v[48:51], v[194:197], v[154:157], v[48:51]
	v_mfma_f32_16x16x32_bf16 v[36:39], v[186:189], v[162:165], v[36:39]
	v_mfma_f32_16x16x32_bf16 v[32:35], v[194:197], v[162:165], v[32:35]
	v_mfma_f32_16x16x32_bf16 v[20:23], v[186:189], v[170:173], v[20:23]
	v_mfma_f32_16x16x32_bf16 v[16:19], v[194:197], v[170:173], v[16:19]
	v_mfma_f32_16x16x32_bf16 v[4:7], v[186:189], v[178:181], v[4:7]
	v_mfma_f32_16x16x32_bf16 v[0:3], v[194:197], v[178:181], v[0:3]
	v_mfma_f32_16x16x32_bf16 v[52:55], v[190:193], v[158:161], v[52:55]
	v_mfma_f32_16x16x32_bf16 v[48:51], v[198:201], v[158:161], v[48:51]
	v_mfma_f32_16x16x32_bf16 v[36:39], v[190:193], v[166:169], v[36:39]
	v_mfma_f32_16x16x32_bf16 v[32:35], v[198:201], v[166:169], v[32:35]
	v_mfma_f32_16x16x32_bf16 v[20:23], v[190:193], v[174:177], v[20:23]
	v_mfma_f32_16x16x32_bf16 v[16:19], v[198:201], v[174:177], v[16:19]
	v_mfma_f32_16x16x32_bf16 v[4:7], v[190:193], v[182:185], v[4:7]
	v_mfma_f32_16x16x32_bf16 v[0:3], v[198:201], v[182:185], v[0:3]
	s_cmp_gt_u32 s6, 29
	s_barrier
	s_cbranch_scc0 .LBB0_74
;   DI void epi(const Acc& acc, const Unit& u, int wr, int wc, int fr, int fq) const {
;     const int cc = u.pn * 64 + 16 * wc + 4 * fq;
;     u32x2 zz[2][4][4];
; #pragma unroll
;     for (int ai = 0; ai < 2; ++ai)
; #pragma unroll
;       for (int m = 0; m < 4; ++m) {
;         const u16* zr = Z + (size_t)(u.pm * 256 + ai * HALF + wr * 64 + m * 16 + fr) * NGATE + cc;
; #pragma unroll
;         for (int br = 0; br < 4; ++br) zz[ai][m][br] = *(const u32x2*)(zr + br * 2048);
;       }
;     f32x4 bg[4];
; #pragma unroll
;     for (int br = 0; br < 4; ++br) bg[br] = *(const f32x4*)(bgate + br * 2048 + cc);
	v_mov_b32_e32 v84, v247
	v_mov_b32_e32 v85, v246
	s_lshl_b32 s0, s44, 6
	s_or_b32 s0, s0, s96
	v_lshl_add_u32 v84, v84, 2, s0
	s_lshl_b32 s0, s64, 8
	s_add_i32 s0, s0, s37
	v_add_u32_e32 v224, s0, v85
	v_ashrrev_i32_e32 v85, 31, v84
	v_lshlrev_b64 v[154:155], 1, v[84:85]
	v_ashrrev_i32_e32 v225, 31, v224
	v_lshl_add_u64 v[86:87], s[26:27], 0, v[154:155]
	v_lshlrev_b64 v[88:89], 14, v[224:225]
	v_lshl_add_u64 v[88:89], v[86:87], 0, v[88:89]
	v_add_co_u32_e32 v90, vcc, s82, v88
	v_add_u32_e32 v212, 16, v224
	s_nop 0
	v_addc_co_u32_e32 v91, vcc, 0, v89, vcc
	v_ashrrev_i32_e32 v213, 31, v212
	v_add_co_u32_e32 v96, vcc, s92, v88
	v_lshlrev_b64 v[98:99], 14, v[212:213]
	s_nop 0
	v_addc_co_u32_e32 v97, vcc, 0, v89, vcc
	v_lshl_add_u64 v[98:99], v[86:87], 0, v[98:99]
	v_add_co_u32_e32 v100, vcc, s82, v98
	v_add_u32_e32 v202, 32, v224
	s_nop 0
	v_addc_co_u32_e32 v101, vcc, 0, v99, vcc
	global_load_dwordx2 v[230:231], v[90:91], off offset:-4096
	global_load_dwordx2 v[226:227], v[90:91], off
	global_load_dwordx2 v[220:221], v[100:101], off offset:-4096
	global_load_dwordx2 v[214:215], v[100:101], off
	v_add_co_u32_e32 v90, vcc, s92, v98
	v_ashrrev_i32_e32 v203, 31, v202
	s_nop 0
	v_addc_co_u32_e32 v91, vcc, 0, v99, vcc
	global_load_dwordx2 v[232:233], v[88:89], off
	global_load_dwordx2 v[228:229], v[96:97], off
	global_load_dwordx2 v[222:223], v[98:99], off
	global_load_dwordx2 v[216:217], v[90:91], off
	v_lshlrev_b64 v[88:89], 14, v[202:203]
	v_lshl_add_u64 v[88:89], v[86:87], 0, v[88:89]
	v_add_co_u32_e32 v90, vcc, s82, v88
	v_add_u32_e32 v190, 48, v224
	s_nop 0
	v_addc_co_u32_e32 v91, vcc, 0, v89, vcc
	v_ashrrev_i32_e32 v191, 31, v190
	v_add_co_u32_e32 v96, vcc, s92, v88
	v_lshlrev_b64 v[98:99], 14, v[190:191]
	s_nop 0
	v_addc_co_u32_e32 v97, vcc, 0, v89, vcc
	v_lshl_add_u64 v[98:99], v[86:87], 0, v[98:99]
	v_add_co_u32_e32 v100, vcc, s82, v98
	v_add_u32_e32 v184, 0x80, v224
	s_nop 0
	v_addc_co_u32_e32 v101, vcc, 0, v99, vcc
	global_load_dwordx2 v[210:211], v[90:91], off offset:-4096
	global_load_dwordx2 v[206:207], v[90:91], off
	global_load_dwordx2 v[200:201], v[100:101], off offset:-4096
	global_load_dwordx2 v[192:193], v[100:101], off
	v_add_co_u32_e32 v90, vcc, s92, v98
	v_lshl_add_u64 v[84:85], v[84:85], 2, s[12:13]
	v_ashrrev_i32_e32 v185, 31, v184
	v_addc_co_u32_e32 v91, vcc, 0, v99, vcc
	global_load_dwordx4 v[100:103], v[84:85], off
	global_load_dwordx2 v[218:219], v[88:89], off
	global_load_dwordx2 v[208:209], v[96:97], off
	global_load_dwordx2 v[204:205], v[98:99], off
	global_load_dwordx2 v[198:199], v[90:91], off
	v_lshlrev_b64 v[88:89], 14, v[184:185]
	v_lshl_add_u64 v[88:89], v[86:87], 0, v[88:89]
	v_add_co_u32_e32 v90, vcc, s82, v88
	v_add_u32_e32 v174, 0x90, v224
	s_nop 0
	v_addc_co_u32_e32 v91, vcc, 0, v89, vcc
	v_add_co_u32_e32 v156, vcc, s92, v88
	v_ashrrev_i32_e32 v175, 31, v174
	s_nop 0
	v_addc_co_u32_e32 v157, vcc, 0, v89, vcc
	v_add_co_u32_e32 v96, vcc, s82, v84
	v_lshlrev_b64 v[158:159], 14, v[174:175]
	s_nop 0
	v_addc_co_u32_e32 v97, vcc, 0, v85, vcc
	global_load_dwordx4 v[96:99], v[96:97], off
	v_lshl_add_u64 v[158:159], v[86:87], 0, v[158:159]
	v_add_co_u32_e32 v160, vcc, s82, v158
	v_add_u32_e32 v164, 0xa0, v224
	s_nop 0
	v_addc_co_u32_e32 v161, vcc, 0, v159, vcc
	global_load_dwordx2 v[194:195], v[90:91], off offset:-4096
	global_load_dwordx2 v[186:187], v[90:91], off
	global_load_dwordx2 v[180:181], v[160:161], off offset:-4096
	global_load_dwordx2 v[176:177], v[160:161], off
	v_add_co_u32_e32 v90, vcc, s92, v158
	v_ashrrev_i32_e32 v165, 31, v164
	s_nop 0
	v_addc_co_u32_e32 v91, vcc, 0, v159, vcc
	global_load_dwordx2 v[196:197], v[88:89], off
	global_load_dwordx2 v[188:189], v[156:157], off
	global_load_dwordx2 v[182:183], v[158:159], off
	global_load_dwordx2 v[178:179], v[90:91], off
	v_lshlrev_b64 v[88:89], 14, v[164:165]
	v_lshl_add_u64 v[162:163], v[86:87], 0, v[88:89]
	v_add_co_u32_e32 v158, vcc, s82, v162
	v_add_u32_e32 v156, 0xb0, v224
	s_nop 0
	v_addc_co_u32_e32 v159, vcc, 0, v163, vcc
	v_add_co_u32_e32 v168, vcc, s92, v162
	v_ashrrev_i32_e32 v157, 31, v156
	s_nop 0
	v_addc_co_u32_e32 v169, vcc, 0, v163, vcc
	v_add_co_u32_e32 v88, vcc, s54, v84
	v_lshlrev_b64 v[160:161], 14, v[156:157]
	s_nop 0
	v_addc_co_u32_e32 v89, vcc, 0, v85, vcc
	global_load_dwordx4 v[88:91], v[88:89], off
	v_lshl_add_u64 v[250:251], v[86:87], 0, v[160:161]
	v_add_co_u32_e32 v86, vcc, s82, v250
	s_mov_b32 s44, s20
	s_nop 0
	v_addc_co_u32_e32 v87, vcc, 0, v251, vcc
	v_add_co_u32_e32 v84, vcc, s55, v84
	global_load_dwordx2 v[170:171], v[158:159], off offset:-4096
	global_load_dwordx2 v[166:167], v[158:159], off
	global_load_dwordx2 v[160:161], v[86:87], off offset:-4096
	s_nop 0
	global_load_dwordx2 v[158:159], v[86:87], off
	v_addc_co_u32_e32 v85, vcc, 0, v85, vcc
	global_load_dwordx4 v[84:87], v[84:85], off
	v_add_co_u32_e32 v252, vcc, s92, v250
	s_mov_b32 s64, s18
	s_nop 0
	v_addc_co_u32_e32 v253, vcc, 0, v251, vcc
	s_and_b64 vcc, exec, s[8:9]
	s_mov_b64 s[66:67], s[62:63]
	s_mov_b64 s[68:69], s[22:23]
	v_readlane_b32 s0, v255, 23
	s_cmpk_gt_u32 s0, 0xff
	s_cbranch_scc1 .Lds_gate_x
	s_barrier

; #define G_STAGE(bufoff, gbase, voff) do { _Pragma("unroll") for (int _i = 0; _i < 2; ++_i) \
;         __builtin_amdgcn_global_load_lds((const unsigned*)((const char*)(gbase) + (voff)[_i]), (LAS unsigned*)(lds + (bufoff) + ldsw + _i * 8192), 16, 0, 0); } while (0)
; #define G_LDA(dst, b, h) do { _Pragma("unroll") for (int m = 0; m < 4; ++m) _Pragma("unroll") for (int k = 0; k < 2; ++k) dst[m][k] = *(const LAS bf16x8*)(lds + G_SA(b, h) + aoff + m * 2048 + k * 1024); } while (0)
; #define G_LDB(dst, b, h) do { _Pragma("unroll") for (int n = 0; n < 2; ++n) _Pragma("unroll") for (int k = 0; k < 2; ++k) dst[n][k] = *(const LAS bf16x8*)(lds + G_SB(b, h) + boff + n * 2048 + k * 1024); } while (0)
; #define G_MMA(ai, bj, At, Bt) do { __builtin_amdgcn_s_setprio(1); _Pragma("unroll") for (int m = 0; m < 4; ++m) _Pragma("unroll") for (int n = 0; n < 2; ++n) _Pragma("unroll") for (int k = 0; k < 2; ++k) \
;         acc[ai][bj][m][n] = __builtin_amdgcn_mfma_f32_16x16x32_bf16(Bt[n][k], At[m][k], acc[ai][bj][m][n], 0, 0, 0); __builtin_amdgcn_s_setprio(0); } while (0)
; #define G_WAIT_V(n) asm volatile("s_waitcnt vmcnt(" #n ")" ::: "memory")
; #define G_WAIT_L(n) asm volatile("s_waitcnt lgkmcnt(" #n ")" ::: "memory")
; #define G_BAR __builtin_amdgcn_s_barrier()
; #define G_SCHED __builtin_amdgcn_sched_barrier(0)
; template <class J>
; DI void gemm_phase(LAS unsigned char* lds, const J& job) {
;     ...
;       G_LDB(B0, 0, 0); G_SCHED; G_LDA(At, 0, 0); G_STAGE(G_SA(1, 1), a1 + hstepA, voffA);
;       G_WAIT_L(8); G_BAR; G_WAIT_L(0); G_MMA(0, 0, At, B0); G_BAR; G_SCHED;
;       G_LDB(B1, 0, 1); G_STAGE(G_SB(0, 0), b2, voffB);
;       G_BAR; G_WAIT_L(0); G_MMA(0, 1, At, B1); G_BAR;
;       G_LDA(At, 0, 1); G_STAGE(G_SA(0, 0), a2, voffA);
;       G_BAR; G_WAIT_L(0); G_MMA(1, 0, At, B0); G_BAR; G_SCHED;
;       G_STAGE(G_SB(0, 1), b2 + hstepB, voffB);
;       G_WAIT_V(6); G_BAR; G_MMA(1, 1, At, B1); G_BAR;
.LBB0_104:
	s_add_i32 s1, s84, 0x100
	ds_read_b128 v[140:143], v208
	ds_read_b128 v[148:151], v208 offset:1024
	ds_read_b128 v[152:155], v208 offset:2048
	ds_read_b128 v[156:159], v208 offset:3072
	s_add_u32 vcc_lo, s9, s0
	s_addc_u32 vcc_hi, s17, 0
	ds_read_b128 v[160:163], v139
	ds_read_b128 v[164:167], v139 offset:1024
	ds_read_b128 v[168:171], v139 offset:2048
	ds_read_b128 v[172:175], v139 offset:3072
	ds_read_b128 v[176:179], v139 offset:4096
	ds_read_b128 v[180:183], v139 offset:5120
	ds_read_b128 v[184:187], v139 offset:6144
	ds_read_b128 v[188:191], v139 offset:7168
	s_waitcnt lgkmcnt(8)
	s_barrier
	s_waitcnt lgkmcnt(0)
	v_mfma_f32_16x16x32_bf16 v[124:127], v[140:143], v[160:163], v[124:127]
	v_mfma_f32_16x16x32_bf16 v[120:123], v[152:155], v[160:163], v[120:123]
	v_mfma_f32_16x16x32_bf16 v[116:119], v[140:143], v[168:171], v[116:119]
	v_mfma_f32_16x16x32_bf16 v[108:111], v[152:155], v[168:171], v[108:111]
	v_mfma_f32_16x16x32_bf16 v[100:103], v[140:143], v[176:179], v[100:103]
	v_mfma_f32_16x16x32_bf16 v[92:95], v[152:155], v[176:179], v[92:95]
	v_mfma_f32_16x16x32_bf16 v[84:87], v[140:143], v[184:187], v[84:87]
	v_mfma_f32_16x16x32_bf16 v[76:79], v[152:155], v[184:187], v[76:79]
	v_mfma_f32_16x16x32_bf16 v[124:127], v[148:151], v[164:167], v[124:127]
	v_mfma_f32_16x16x32_bf16 v[120:123], v[156:159], v[164:167], v[120:123]
	v_mfma_f32_16x16x32_bf16 v[116:119], v[148:151], v[172:175], v[116:119]
	v_mfma_f32_16x16x32_bf16 v[108:111], v[156:159], v[172:175], v[108:111]
	v_mfma_f32_16x16x32_bf16 v[100:103], v[148:151], v[180:183], v[100:103]
	v_mfma_f32_16x16x32_bf16 v[92:95], v[156:159], v[180:183], v[92:95]
	v_mfma_f32_16x16x32_bf16 v[84:87], v[148:151], v[188:191], v[84:87]
	v_mfma_f32_16x16x32_bf16 v[76:79], v[156:159], v[188:191], v[76:79]
	s_barrier
	s_add_i32 m0, s25, 0xc000
	s_nop 0
	global_load_lds_dwordx4 v132, vcc
	s_add_i32 m0, s25, 0xe000
	s_nop 0
	global_load_lds_dwordx4 v130, vcc
	s_add_i32 s0, s85, 0x100
	s_add_i32 s1, s1, s24
	ds_read_b128 v[192:195], v208 offset:16384
	ds_read_b128 v[196:199], v208 offset:17408
	ds_read_b128 v[200:203], v208 offset:18432
	ds_read_b128 v[204:207], v208 offset:19456
	s_mov_b32 m0, s1
	s_nop 0
	global_load_lds_dwordx4 v146, s[72:73]
	s_add_i32 m0, s1, 0x2000
	s_nop 0
	global_load_lds_dwordx4 v128, s[72:73]
	s_barrier
	s_waitcnt lgkmcnt(0)
	v_mfma_f32_16x16x32_bf16 v[112:115], v[192:195], v[160:163], v[112:115]
	v_mfma_f32_16x16x32_bf16 v[104:107], v[200:203], v[160:163], v[104:107]
	v_mfma_f32_16x16x32_bf16 v[96:99], v[192:195], v[168:171], v[96:99]
	v_mfma_f32_16x16x32_bf16 v[88:91], v[200:203], v[168:171], v[88:91]
	v_mfma_f32_16x16x32_bf16 v[80:83], v[192:195], v[176:179], v[80:83]
	v_mfma_f32_16x16x32_bf16 v[72:75], v[200:203], v[176:179], v[72:75]
	v_mfma_f32_16x16x32_bf16 v[68:71], v[192:195], v[184:187], v[68:71]
	v_mfma_f32_16x16x32_bf16 v[64:67], v[200:203], v[184:187], v[64:67]
	v_mfma_f32_16x16x32_bf16 v[112:115], v[196:199], v[164:167], v[112:115]
	v_mfma_f32_16x16x32_bf16 v[104:107], v[204:207], v[164:167], v[104:107]
	v_mfma_f32_16x16x32_bf16 v[96:99], v[196:199], v[172:175], v[96:99]
	v_mfma_f32_16x16x32_bf16 v[88:91], v[204:207], v[172:175], v[88:91]
	v_mfma_f32_16x16x32_bf16 v[80:83], v[196:199], v[180:183], v[80:83]
	v_mfma_f32_16x16x32_bf16 v[72:75], v[204:207], v[180:183], v[72:75]
	v_mfma_f32_16x16x32_bf16 v[68:71], v[196:199], v[188:191], v[68:71]
	v_mfma_f32_16x16x32_bf16 v[64:67], v[204:207], v[188:191], v[64:67]
	s_mov_b32 m0, s25
	s_barrier
	ds_read_b128 v[160:163], v139 offset:16384
	ds_read_b128 v[164:167], v139 offset:17408
	ds_read_b128 v[168:171], v139 offset:18432
	ds_read_b128 v[172:175], v139 offset:19456
	ds_read_b128 v[176:179], v139 offset:20480
	ds_read_b128 v[180:183], v139 offset:21504
	ds_read_b128 v[184:187], v139 offset:22528
	ds_read_b128 v[188:191], v139 offset:23552
	global_load_lds_dwordx4 v132, s[70:71]
	s_mov_b32 m0, s36
	s_nop 0
	global_load_lds_dwordx4 v130, s[70:71]
	s_barrier
	s_waitcnt lgkmcnt(0)
	v_mfma_f32_16x16x32_bf16 v[60:63], v[140:143], v[160:163], v[60:63]
	v_mfma_f32_16x16x32_bf16 v[56:59], v[152:155], v[160:163], v[56:59]
	v_mfma_f32_16x16x32_bf16 v[52:55], v[140:143], v[168:171], v[52:55]
	v_mfma_f32_16x16x32_bf16 v[44:47], v[152:155], v[168:171], v[44:47]
	v_mfma_f32_16x16x32_bf16 v[36:39], v[140:143], v[176:179], v[36:39]
	v_mfma_f32_16x16x32_bf16 v[28:31], v[152:155], v[176:179], v[28:31]
	v_mfma_f32_16x16x32_bf16 v[20:23], v[140:143], v[184:187], v[20:23]
	v_mfma_f32_16x16x32_bf16 v[12:15], v[152:155], v[184:187], v[12:15]
	v_mfma_f32_16x16x32_bf16 v[60:63], v[148:151], v[164:167], v[60:63]
	v_mfma_f32_16x16x32_bf16 v[56:59], v[156:159], v[164:167], v[56:59]
	v_mfma_f32_16x16x32_bf16 v[52:55], v[148:151], v[172:175], v[52:55]
	v_mfma_f32_16x16x32_bf16 v[44:47], v[156:159], v[172:175], v[44:47]
	v_mfma_f32_16x16x32_bf16 v[36:39], v[148:151], v[180:183], v[36:39]
	v_mfma_f32_16x16x32_bf16 v[28:31], v[156:159], v[180:183], v[28:31]
	v_mfma_f32_16x16x32_bf16 v[20:23], v[148:151], v[188:191], v[20:23]
	v_mfma_f32_16x16x32_bf16 v[12:15], v[156:159], v[188:191], v[12:15]
	s_barrier
	s_add_u32 s72, s72, 0x20000
	s_addc_u32 s73, s73, 0
	s_add_i32 s0, s0, s24
	s_mov_b32 m0, s0
	s_nop 0
	global_load_lds_dwordx4 v146, s[72:73]
	s_add_i32 m0, s0, 0x2000
	s_nop 0
	global_load_lds_dwordx4 v128, s[72:73]
	s_waitcnt vmcnt(6)
	s_barrier
; #define G_STAGE(bufoff, gbase, voff) do { _Pragma("unroll") for (int _i = 0; _i < 2; ++_i) \
;         __builtin_amdgcn_global_load_lds((const unsigned*)((const char*)(gbase) + (voff)[_i]), (LAS unsigned*)(lds + (bufoff) + ldsw + _i * 8192), 16, 0, 0); } while (0)
; #define G_LDA(dst, b, h) do { _Pragma("unroll") for (int m = 0; m < 4; ++m) _Pragma("unroll") for (int k = 0; k < 2; ++k) dst[m][k] = *(const LAS bf16x8*)(lds + G_SA(b, h) + aoff + m * 2048 + k * 1024); } while (0)
; #define G_LDB(dst, b, h) do { _Pragma("unroll") for (int n = 0; n < 2; ++n) _Pragma("unroll") for (int k = 0; k < 2; ++k) dst[n][k] = *(const LAS bf16x8*)(lds + G_SB(b, h) + boff + n * 2048 + k * 1024); } while (0)
; #define G_MMA(ai, bj, At, Bt) do { __builtin_amdgcn_s_setprio(1); _Pragma("unroll") for (int m = 0; m < 4; ++m) _Pragma("unroll") for (int n = 0; n < 2; ++n) _Pragma("unroll") for (int k = 0; k < 2; ++k) \
;         acc[ai][bj][m][n] = __builtin_amdgcn_mfma_f32_16x16x32_bf16(Bt[n][k], At[m][k], acc[ai][bj][m][n], 0, 0, 0); __builtin_amdgcn_s_setprio(0); } while (0)
; #define G_WAIT_V(n) asm volatile("s_waitcnt vmcnt(" #n ")" ::: "memory")
; #define G_WAIT_L(n) asm volatile("s_waitcnt lgkmcnt(" #n ")" ::: "memory")
; #define G_BAR __builtin_amdgcn_s_barrier()
; #define G_SCHED __builtin_amdgcn_sched_barrier(0)
; template <class J>
; DI void gemm_phase(LAS unsigned char* lds, const J& job) {
;     ...
;       G_WAIT_V(6); G_BAR; G_MMA(1, 1, At, B1); G_BAR;
;       G_LDB(B0, 1, 0); G_SCHED; G_LDA(At, 1, 0); G_STAGE(G_SA(0, 1), a2 + hstepA, voffA);
;       G_WAIT_L(8); G_BAR; G_WAIT_L(0); G_MMA(0, 0, At, B0); G_BAR; G_SCHED;
;       G_LDB(B1, 1, 1); G_STAGE(G_SB(1, 0), b3, voffB);
;       G_BAR; G_WAIT_L(0); G_MMA(0, 1, At, B1); G_BAR;
;       G_LDA(At, 1, 1); G_STAGE(G_SA(1, 0), a3, voffA);
;       G_BAR; G_WAIT_L(0); G_MMA(1, 0, At, B0); G_BAR; G_SCHED;
	v_mfma_f32_16x16x32_bf16 v[48:51], v[192:195], v[160:163], v[48:51]
	v_mfma_f32_16x16x32_bf16 v[40:43], v[200:203], v[160:163], v[40:43]
	v_mfma_f32_16x16x32_bf16 v[32:35], v[192:195], v[168:171], v[32:35]
	v_mfma_f32_16x16x32_bf16 v[24:27], v[200:203], v[168:171], v[24:27]
	v_mfma_f32_16x16x32_bf16 v[16:19], v[192:195], v[176:179], v[16:19]
	v_mfma_f32_16x16x32_bf16 v[8:11], v[200:203], v[176:179], v[8:11]
	v_mfma_f32_16x16x32_bf16 v[4:7], v[192:195], v[184:187], v[4:7]
	v_mfma_f32_16x16x32_bf16 v[0:3], v[200:203], v[184:187], v[0:3]
	v_mfma_f32_16x16x32_bf16 v[48:51], v[196:199], v[164:167], v[48:51]
	v_mfma_f32_16x16x32_bf16 v[40:43], v[204:207], v[164:167], v[40:43]
	v_mfma_f32_16x16x32_bf16 v[32:35], v[196:199], v[172:175], v[32:35]
	v_mfma_f32_16x16x32_bf16 v[24:27], v[204:207], v[172:175], v[24:27]
	v_mfma_f32_16x16x32_bf16 v[16:19], v[196:199], v[180:183], v[16:19]
	v_mfma_f32_16x16x32_bf16 v[8:11], v[204:207], v[180:183], v[8:11]
	v_mfma_f32_16x16x32_bf16 v[4:7], v[196:199], v[188:191], v[4:7]
	v_mfma_f32_16x16x32_bf16 v[0:3], v[204:207], v[188:191], v[0:3]
	s_add_i32 s0, s88, 0x100
	s_barrier
	ds_read_b128 v[140:143], v208 offset:32768
	ds_read_b128 v[148:151], v208 offset:33792
	ds_read_b128 v[152:155], v208 offset:34816
	ds_read_b128 v[156:159], v208 offset:35840
	s_add_u32 s70, s70, 0x80000
	s_addc_u32 s71, s71, 0
	ds_read_b128 v[160:163], v139 offset:32768
	ds_read_b128 v[164:167], v139 offset:33792
	ds_read_b128 v[168:171], v139 offset:34816
	ds_read_b128 v[172:175], v139 offset:35840
	ds_read_b128 v[176:179], v139 offset:36864
	ds_read_b128 v[180:183], v139 offset:37888
	ds_read_b128 v[184:187], v139 offset:38912
	ds_read_b128 v[188:191], v139 offset:39936
	s_waitcnt lgkmcnt(8)
	s_barrier
	s_waitcnt lgkmcnt(0)
	v_mfma_f32_16x16x32_bf16 v[124:127], v[140:143], v[160:163], v[124:127]
	v_mfma_f32_16x16x32_bf16 v[120:123], v[152:155], v[160:163], v[120:123]
	v_mfma_f32_16x16x32_bf16 v[116:119], v[140:143], v[168:171], v[116:119]
	v_mfma_f32_16x16x32_bf16 v[108:111], v[152:155], v[168:171], v[108:111]
	v_mfma_f32_16x16x32_bf16 v[100:103], v[140:143], v[176:179], v[100:103]
	v_mfma_f32_16x16x32_bf16 v[92:95], v[152:155], v[176:179], v[92:95]
	v_mfma_f32_16x16x32_bf16 v[84:87], v[140:143], v[184:187], v[84:87]
	v_mfma_f32_16x16x32_bf16 v[76:79], v[152:155], v[184:187], v[76:79]
	v_mfma_f32_16x16x32_bf16 v[124:127], v[148:151], v[164:167], v[124:127]
	v_mfma_f32_16x16x32_bf16 v[120:123], v[156:159], v[164:167], v[120:123]
	v_mfma_f32_16x16x32_bf16 v[116:119], v[148:151], v[172:175], v[116:119]
	v_mfma_f32_16x16x32_bf16 v[108:111], v[156:159], v[172:175], v[108:111]
	v_mfma_f32_16x16x32_bf16 v[100:103], v[148:151], v[180:183], v[100:103]
	v_mfma_f32_16x16x32_bf16 v[92:95], v[156:159], v[180:183], v[92:95]
	v_mfma_f32_16x16x32_bf16 v[84:87], v[148:151], v[188:191], v[84:87]
	v_mfma_f32_16x16x32_bf16 v[76:79], v[156:159], v[188:191], v[76:79]
	s_barrier
	s_mov_b32 m0, s37
	s_nop 0
	global_load_lds_dwordx4 v132, s[70:71]
	s_mov_b32 m0, s38
	s_nop 0
	global_load_lds_dwordx4 v130, s[70:71]
	s_add_i32 s1, s89, 0x100
	s_add_i32 s0, s0, s24
	ds_read_b128 v[192:195], v208 offset:49152
	ds_read_b128 v[196:199], v208 offset:50176
	ds_read_b128 v[200:203], v208 offset:51200
	ds_read_b128 v[204:207], v208 offset:52224
	s_mov_b32 m0, s0
	s_nop 0
	global_load_lds_dwordx4 v146, s[66:67]
	s_add_i32 m0, s0, 0x2000
	s_nop 0
	global_load_lds_dwordx4 v128, s[66:67]
	s_barrier
	s_waitcnt lgkmcnt(0)
	v_mfma_f32_16x16x32_bf16 v[112:115], v[192:195], v[160:163], v[112:115]
	v_mfma_f32_16x16x32_bf16 v[104:107], v[200:203], v[160:163], v[104:107]
	v_mfma_f32_16x16x32_bf16 v[96:99], v[192:195], v[168:171], v[96:99]
	v_mfma_f32_16x16x32_bf16 v[88:91], v[200:203], v[168:171], v[88:91]
	v_mfma_f32_16x16x32_bf16 v[80:83], v[192:195], v[176:179], v[80:83]
	v_mfma_f32_16x16x32_bf16 v[72:75], v[200:203], v[176:179], v[72:75]
	v_mfma_f32_16x16x32_bf16 v[68:71], v[192:195], v[184:187], v[68:71]
	v_mfma_f32_16x16x32_bf16 v[64:67], v[200:203], v[184:187], v[64:67]
	v_mfma_f32_16x16x32_bf16 v[112:115], v[196:199], v[164:167], v[112:115]
	v_mfma_f32_16x16x32_bf16 v[104:107], v[204:207], v[164:167], v[104:107]
	v_mfma_f32_16x16x32_bf16 v[96:99], v[196:199], v[172:175], v[96:99]
	v_mfma_f32_16x16x32_bf16 v[88:91], v[204:207], v[172:175], v[88:91]
	v_mfma_f32_16x16x32_bf16 v[80:83], v[196:199], v[180:183], v[80:83]
	v_mfma_f32_16x16x32_bf16 v[72:75], v[204:207], v[180:183], v[72:75]
	v_mfma_f32_16x16x32_bf16 v[68:71], v[196:199], v[188:191], v[68:71]
	v_mfma_f32_16x16x32_bf16 v[64:67], v[204:207], v[188:191], v[64:67]
	s_mov_b32 m0, s75
	s_barrier
	ds_read_b128 v[160:163], v139 offset:49152
	ds_read_b128 v[164:167], v139 offset:50176
	ds_read_b128 v[168:171], v139 offset:51200
	ds_read_b128 v[172:175], v139 offset:52224
	ds_read_b128 v[176:179], v139 offset:53248
	ds_read_b128 v[180:183], v139 offset:54272
	ds_read_b128 v[184:187], v139 offset:55296
	ds_read_b128 v[188:191], v139 offset:56320
	global_load_lds_dwordx4 v132, s[68:69]
	s_mov_b32 m0, s76
	s_nop 0
	global_load_lds_dwordx4 v130, s[68:69]
	s_barrier
	s_waitcnt lgkmcnt(0)
	v_mfma_f32_16x16x32_bf16 v[60:63], v[140:143], v[160:163], v[60:63]
	v_mfma_f32_16x16x32_bf16 v[56:59], v[152:155], v[160:163], v[56:59]
	v_mfma_f32_16x16x32_bf16 v[52:55], v[140:143], v[168:171], v[52:55]
	v_mfma_f32_16x16x32_bf16 v[44:47], v[152:155], v[168:171], v[44:47]
	v_mfma_f32_16x16x32_bf16 v[36:39], v[140:143], v[176:179], v[36:39]
	v_mfma_f32_16x16x32_bf16 v[28:31], v[152:155], v[176:179], v[28:31]
	v_mfma_f32_16x16x32_bf16 v[20:23], v[140:143], v[184:187], v[20:23]
	v_mfma_f32_16x16x32_bf16 v[12:15], v[152:155], v[184:187], v[12:15]
	v_mfma_f32_16x16x32_bf16 v[60:63], v[148:151], v[164:167], v[60:63]
	v_mfma_f32_16x16x32_bf16 v[56:59], v[156:159], v[164:167], v[56:59]
	v_mfma_f32_16x16x32_bf16 v[52:55], v[148:151], v[172:175], v[52:55]
	v_mfma_f32_16x16x32_bf16 v[44:47], v[156:159], v[172:175], v[44:47]
	v_mfma_f32_16x16x32_bf16 v[36:39], v[148:151], v[180:183], v[36:39]
	v_mfma_f32_16x16x32_bf16 v[28:31], v[156:159], v[180:183], v[28:31]
	v_mfma_f32_16x16x32_bf16 v[20:23], v[148:151], v[188:191], v[20:23]
	v_mfma_f32_16x16x32_bf16 v[12:15], v[156:159], v[188:191], v[12:15]
	s_barrier
; #define G_STAGE(bufoff, gbase, voff) do { _Pragma("unroll") for (int _i = 0; _i < 2; ++_i) \
;         __builtin_amdgcn_global_load_lds((const unsigned*)((const char*)(gbase) + (voff)[_i]), (LAS unsigned*)(lds + (bufoff) + ldsw + _i * 8192), 16, 0, 0); } while (0)
; #define G_MMA(ai, bj, At, Bt) do { __builtin_amdgcn_s_setprio(1); _Pragma("unroll") for (int m = 0; m < 4; ++m) _Pragma("unroll") for (int n = 0; n < 2; ++n) _Pragma("unroll") for (int k = 0; k < 2; ++k) \
;         acc[ai][bj][m][n] = __builtin_amdgcn_mfma_f32_16x16x32_bf16(Bt[n][k], At[m][k], acc[ai][bj][m][n], 0, 0, 0); __builtin_amdgcn_s_setprio(0); } while (0)
; #define G_WAIT_V(n) asm volatile("s_waitcnt vmcnt(" #n ")" ::: "memory")
; #define G_BAR __builtin_amdgcn_s_barrier()
; template <class J>
; DI void gemm_phase(LAS unsigned char* lds, const J& job) {
;     ...
;     for (int t = 0; t < nt; t += 2) {
;       const bool last = (t == nt - 2);
;       const char* a1 = cA + G_KT(t + 1);
;       const char* a2 = last ? nA + G_KT(0) : cA + G_KT(t + 2); const char* b2 = last ? nB + G_KT(0) : cB + G_KT(t + 2);
;       const char* a3 = last ? nA + G_KT(1) : cA + G_KT(t + 3); const char* b3 = last ? nB + G_KT(1) : cB + G_KT(t + 3);
;     ...
;       G_STAGE(G_SB(1, 1), b3 + hstepB, voffB);
;       G_WAIT_V(6); G_BAR; G_MMA(1, 1, At, B1); G_BAR;
	s_add_u32 s66, s66, 0x20000
	s_addc_u32 s67, s67, 0
	s_add_i32 s0, s1, s24
	s_mov_b32 m0, s0
	s_nop 0
	global_load_lds_dwordx4 v146, s[66:67]
	s_add_i32 m0, s0, 0x2000
	s_nop 0
	global_load_lds_dwordx4 v128, s[66:67]
	s_add_i32 s6, s6, 2
	s_addk_i32 s56, 0x100
	s_addk_i32 s7, 0x100
	s_add_i32 s1, s56, 0xffffff80
	s_and_b32 s0, s7, 0x380
	s_and_b32 s1, s1, 0x380
	s_add_u32 s57, s64, s1
	s_addc_u32 s66, s65, 0
	s_add_u32 s1, s62, s1
	s_addc_u32 s67, s63, 0
	s_and_b32 s68, s56, 0x380
	s_add_u32 s80, s64, s68
	s_addc_u32 s69, s65, 0
	s_add_u32 s97, s62, s68
	s_addc_u32 vcc_lo, s63, 0
	s_cmp_eq_u32 s6, 4
	s_cselect_b32 s71, s83, s66
	s_cselect_b32 s70, s47, s57
	s_cselect_b32 s73, s87, s67
	s_cselect_b32 s72, s86, s1
	s_cselect_b32 s69, s94, s69
	s_cselect_b32 s68, s33, s80
	s_cselect_b32 s67, s5, vcc_lo
	s_cselect_b32 s66, s96, s97
	s_waitcnt vmcnt(6)
	s_barrier
	v_mfma_f32_16x16x32_bf16 v[48:51], v[192:195], v[160:163], v[48:51]
	v_mfma_f32_16x16x32_bf16 v[40:43], v[200:203], v[160:163], v[40:43]
	v_mfma_f32_16x16x32_bf16 v[32:35], v[192:195], v[168:171], v[32:35]
	v_mfma_f32_16x16x32_bf16 v[24:27], v[200:203], v[168:171], v[24:27]
	v_mfma_f32_16x16x32_bf16 v[16:19], v[192:195], v[176:179], v[16:19]
	v_mfma_f32_16x16x32_bf16 v[8:11], v[200:203], v[176:179], v[8:11]
	v_mfma_f32_16x16x32_bf16 v[4:7], v[192:195], v[184:187], v[4:7]
	v_mfma_f32_16x16x32_bf16 v[0:3], v[200:203], v[184:187], v[0:3]
	v_mfma_f32_16x16x32_bf16 v[48:51], v[196:199], v[164:167], v[48:51]
	v_mfma_f32_16x16x32_bf16 v[40:43], v[204:207], v[164:167], v[40:43]
	v_mfma_f32_16x16x32_bf16 v[32:35], v[196:199], v[172:175], v[32:35]
	v_mfma_f32_16x16x32_bf16 v[24:27], v[204:207], v[172:175], v[24:27]
	v_mfma_f32_16x16x32_bf16 v[16:19], v[196:199], v[180:183], v[16:19]
	v_mfma_f32_16x16x32_bf16 v[8:11], v[204:207], v[180:183], v[8:11]
	v_mfma_f32_16x16x32_bf16 v[4:7], v[196:199], v[188:191], v[4:7]
	v_mfma_f32_16x16x32_bf16 v[0:3], v[204:207], v[188:191], v[0:3]
	s_cmp_gt_u32 s6, 5
	s_barrier
	s_cbranch_scc0 .LBB0_104
; DI unsigned pk2(float lo, float hi) { unsigned r; asm("v_cvt_pk_bf16_f32 %0, %1, %2" : "=v"(r) : "v"(lo), "v"(hi)); return r; }
; #define G_WAIT_V(n) asm volatile("s_waitcnt vmcnt(" #n ")" ::: "memory")
; #define G_BAR __builtin_amdgcn_s_barrier()
; template <class J>
; DI void gemm_phase(LAS unsigned char* lds, const J& job) {
;     ...
;     if (!has_next) break;
; #pragma unroll
;     for (int a = 0; a < 2; ++a)
; #pragma unroll
;       for (int b = 0; b < 2; ++b)
; #pragma unroll
;         for (int m = 0; m < 4; ++m)
; #pragma unroll
;           for (int n = 0; n < 2; ++n) acc[a][b][m][n] = (f32x4){0.f, 0.f, 0.f, 0.f};
;     cur = nxt; cA = nA; cB = nB; ++ui;
;   }
;   G_WAIT_V(0);
;   if (wr == 0) G_BAR;
;   DI void epi(const Acc& acc, const Unit& u, int wr, int wc, int fr, int fq) const {
; #pragma unroll
;     for (int ai = 0; ai < 2; ++ai)
; #pragma unroll
;       for (int m = 0; m < 4; ++m) {
;         const int row = u.pm * 256 + ai * HALF + wr * 64 + m * 16 + fr;
; #pragma unroll
;         for (int bj = 0; bj < 2; ++bj) {
;           const int col = u.pn * 256 + bj * HALF + wc * 32 + 8 * fq;
;           const f32x4 v0 = acc[ai][bj][m][0], v1 = acc[ai][bj][m][1];
;           u32x4 o; o.x = pk2(v0.x, v0.y); o.y = pk2(v0.z, v0.w); o.z = pk2(v1.x, v1.y); o.w = pk2(v1.z, v1.w);
;           *(u32x4*)(Z + (size_t)row * NGATE + col) = o;
;         }
;       }
;   }
	v_mov_b32_e32 v135, v137
	v_mov_b32_e32 v134, v136
	s_lshl_b32 s0, s22, 8
	s_add_i32 s0, s0, s44
	v_add_u32_e32 v134, s0, v134
	s_lshl_b32 s0, s46, 8
	s_or_b32 s0, s0, s45
	v_cvt_pk_bf16_f32 v68, v68, v69
	v_cvt_pk_bf16_f32 v69, v70, v71
	v_cvt_pk_bf16_f32 v70, v64, v65
	v_add_u32_e32 v64, 0x80, v134
	v_lshl_add_u32 v140, v135, 3, s0
	v_ashrrev_i32_e32 v135, 31, v134
	v_ashrrev_i32_e32 v65, 31, v64
	v_lshlrev_b64 v[142:143], 14, v[134:135]
	v_ashrrev_i32_e32 v141, 31, v140
	v_lshlrev_b64 v[64:65], 14, v[64:65]
	v_cvt_pk_bf16_f32 v124, v124, v125
	v_cvt_pk_bf16_f32 v125, v126, v127
	v_cvt_pk_bf16_f32 v126, v120, v121
	v_cvt_pk_bf16_f32 v127, v122, v123
	v_lshl_add_u64 v[122:123], s[26:27], 0, v[142:143]
	v_lshlrev_b64 v[120:121], 1, v[140:141]
	v_cvt_pk_bf16_f32 v112, v112, v113
	v_cvt_pk_bf16_f32 v113, v114, v115
	v_cvt_pk_bf16_f32 v114, v104, v105
	v_add_u32_e32 v104, 16, v134
	v_cvt_pk_bf16_f32 v60, v60, v61
	v_cvt_pk_bf16_f32 v61, v62, v63
	v_cvt_pk_bf16_f32 v62, v56, v57
	v_lshl_add_u64 v[56:57], s[26:27], 0, v[64:65]
	v_cvt_pk_bf16_f32 v48, v48, v49
	v_cvt_pk_bf16_f32 v49, v50, v51
	v_cvt_pk_bf16_f32 v50, v40, v41
	v_add_u32_e32 v40, 0x90, v134
	v_lshl_add_u64 v[122:123], v[122:123], 0, v[120:121]
	v_ashrrev_i32_e32 v105, 31, v104
	v_lshl_add_u64 v[56:57], v[56:57], 0, v[120:121]
	v_ashrrev_i32_e32 v41, 31, v40
	v_cvt_pk_bf16_f32 v115, v106, v107
	global_store_dwordx4 v[122:123], v[112:115], off offset:256
	v_cvt_pk_bf16_f32 v51, v42, v43
	global_store_dwordx4 v[56:57], v[48:51], off offset:256
	v_cvt_pk_bf16_f32 v106, v108, v109
	v_cvt_pk_bf16_f32 v96, v96, v97
	v_cvt_pk_bf16_f32 v97, v98, v99
	s_nop 0
	v_lshlrev_b64 v[112:113], 14, v[104:105]
	v_lshl_add_u64 v[108:109], s[26:27], 0, v[112:113]
	v_lshlrev_b64 v[48:49], 14, v[40:41]
	v_cvt_pk_bf16_f32 v98, v88, v89
	v_add_u32_e32 v88, 32, v134
	v_cvt_pk_bf16_f32 v42, v44, v45
	v_lshl_add_u64 v[44:45], s[26:27], 0, v[48:49]
	v_cvt_pk_bf16_f32 v32, v32, v33
	v_cvt_pk_bf16_f32 v33, v34, v35
	v_cvt_pk_bf16_f32 v34, v24, v25
	v_add_u32_e32 v24, 0xa0, v134
	v_lshl_add_u64 v[108:109], v[108:109], 0, v[120:121]
	v_ashrrev_i32_e32 v89, 31, v88
	v_lshl_add_u64 v[44:45], v[44:45], 0, v[120:121]
	v_ashrrev_i32_e32 v25, 31, v24
	v_cvt_pk_bf16_f32 v99, v90, v91
	global_store_dwordx4 v[108:109], v[96:99], off offset:256
	v_cvt_pk_bf16_f32 v35, v26, v27
	global_store_dwordx4 v[44:45], v[32:35], off offset:256
	v_cvt_pk_bf16_f32 v90, v92, v93
	v_cvt_pk_bf16_f32 v80, v80, v81
	v_cvt_pk_bf16_f32 v81, v82, v83
	s_nop 0
	v_lshlrev_b64 v[96:97], 14, v[88:89]
	v_lshl_add_u64 v[92:93], s[26:27], 0, v[96:97]
	v_lshlrev_b64 v[32:33], 14, v[24:25]
	v_cvt_pk_bf16_f32 v82, v72, v73
	v_add_u32_e32 v72, 48, v134
	v_cvt_pk_bf16_f32 v26, v28, v29
	v_lshl_add_u64 v[28:29], s[26:27], 0, v[32:33]
	v_cvt_pk_bf16_f32 v16, v16, v17
	v_cvt_pk_bf16_f32 v17, v18, v19
	v_cvt_pk_bf16_f32 v18, v8, v9
	v_add_u32_e32 v8, 0xb0, v134
	v_lshl_add_u64 v[92:93], v[92:93], 0, v[120:121]
	v_ashrrev_i32_e32 v73, 31, v72
	v_lshl_add_u64 v[28:29], v[28:29], 0, v[120:121]
	v_ashrrev_i32_e32 v9, 31, v8
	v_cvt_pk_bf16_f32 v83, v74, v75
	global_store_dwordx4 v[92:93], v[80:83], off offset:256
	v_cvt_pk_bf16_f32 v19, v10, v11
	global_store_dwordx4 v[28:29], v[16:19], off offset:256
	v_cvt_pk_bf16_f32 v74, v76, v77
	v_cvt_pk_bf16_f32 v10, v12, v13
	s_and_b64 vcc, exec, s[12:13]
	v_lshlrev_b64 v[80:81], 14, v[72:73]
	v_lshlrev_b64 v[16:17], 14, v[8:9]
	v_lshl_add_u64 v[76:77], s[26:27], 0, v[80:81]
	v_lshl_add_u64 v[12:13], s[26:27], 0, v[16:17]
	v_lshl_add_u64 v[76:77], v[76:77], 0, v[120:121]
	v_lshl_add_u64 v[12:13], v[12:13], 0, v[120:121]
	s_mov_b32 s46, s8
	s_mov_b32 s22, s16
	s_mov_b64 s[62:63], s[20:21]
	s_mov_b64 s[64:65], s[18:19]
	global_store_dwordx4 v[122:123], v[124:127], off
	v_cvt_pk_bf16_f32 v104, v116, v117
	v_cvt_pk_bf16_f32 v105, v118, v119
	v_cvt_pk_bf16_f32 v107, v110, v111
	global_store_dwordx4 v[108:109], v[104:107], off
	v_cvt_pk_bf16_f32 v88, v100, v101
	v_cvt_pk_bf16_f32 v89, v102, v103
	v_cvt_pk_bf16_f32 v91, v94, v95
	global_store_dwordx4 v[92:93], v[88:91], off
	v_cvt_pk_bf16_f32 v72, v84, v85
	v_cvt_pk_bf16_f32 v73, v86, v87
	v_cvt_pk_bf16_f32 v75, v78, v79
	global_store_dwordx4 v[76:77], v[72:75], off
	v_cvt_pk_bf16_f32 v71, v66, v67
	global_store_dwordx4 v[76:77], v[68:71], off offset:256
	v_cvt_pk_bf16_f32 v63, v58, v59
	global_store_dwordx4 v[56:57], v[60:63], off
	v_cvt_pk_bf16_f32 v40, v52, v53
	v_cvt_pk_bf16_f32 v41, v54, v55
	v_cvt_pk_bf16_f32 v43, v46, v47
	global_store_dwordx4 v[44:45], v[40:43], off
	v_cvt_pk_bf16_f32 v24, v36, v37
	v_cvt_pk_bf16_f32 v25, v38, v39
	v_cvt_pk_bf16_f32 v27, v30, v31
	global_store_dwordx4 v[28:29], v[24:27], off
	v_cvt_pk_bf16_f32 v8, v20, v21
	v_cvt_pk_bf16_f32 v9, v22, v23
	v_cvt_pk_bf16_f32 v11, v14, v15
	global_store_dwordx4 v[12:13], v[8:11], off
	v_cvt_pk_bf16_f32 v4, v4, v5
	v_cvt_pk_bf16_f32 v5, v6, v7
	v_cvt_pk_bf16_f32 v6, v0, v1
	v_cvt_pk_bf16_f32 v7, v2, v3
	global_store_dwordx4 v[12:13], v[4:7], off offset:256
	s_cbranch_vccz .LBB0_101
	s_setprio 0
	s_waitcnt vmcnt(0)
	v_readlane_b32 s44, v255, 6
	s_cmpk_gt_u32 s4, 0xff
	v_readlane_b32 s45, v255, 7
	s_cbranch_scc1 .LBB0_108
	s_barrier

; #define G_STAGE(bufoff, gbase, voff) do { _Pragma("unroll") for (int _i = 0; _i < 2; ++_i) \
;         __builtin_amdgcn_global_load_lds((const unsigned*)((const char*)(gbase) + (voff)[_i]), (LAS unsigned*)(lds + (bufoff) + ldsw + _i * 8192), 16, 0, 0); } while (0)
; #define G_LDA(dst, b, h) do { _Pragma("unroll") for (int m = 0; m < 4; ++m) _Pragma("unroll") for (int k = 0; k < 2; ++k) dst[m][k] = *(const LAS bf16x8*)(lds + G_SA(b, h) + aoff + m * 2048 + k * 1024); } while (0)
; #define G_LDB(dst, b, h) do { _Pragma("unroll") for (int n = 0; n < 2; ++n) _Pragma("unroll") for (int k = 0; k < 2; ++k) dst[n][k] = *(const LAS bf16x8*)(lds + G_SB(b, h) + boff + n * 2048 + k * 1024); } while (0)
; #define G_MMA(ai, bj, At, Bt) do { __builtin_amdgcn_s_setprio(1); _Pragma("unroll") for (int m = 0; m < 4; ++m) _Pragma("unroll") for (int n = 0; n < 2; ++n) _Pragma("unroll") for (int k = 0; k < 2; ++k) \
;         acc[ai][bj][m][n] = __builtin_amdgcn_mfma_f32_16x16x32_bf16(Bt[n][k], At[m][k], acc[ai][bj][m][n], 0, 0, 0); __builtin_amdgcn_s_setprio(0); } while (0)
; #define G_WAIT_V(n) asm volatile("s_waitcnt vmcnt(" #n ")" ::: "memory")
; #define G_WAIT_L(n) asm volatile("s_waitcnt lgkmcnt(" #n ")" ::: "memory")
; #define G_BAR __builtin_amdgcn_s_barrier()
; #define G_SCHED __builtin_amdgcn_sched_barrier(0)
; template <class J>
; DI void gemm_phase(LAS unsigned char* lds, const J& job) {
;     ...
;       G_LDB(B0, 0, 0); G_SCHED; G_LDA(At, 0, 0); G_STAGE(G_SA(1, 1), a1 + hstepA, voffA);
;       G_WAIT_L(8); G_BAR; G_WAIT_L(0); G_MMA(0, 0, At, B0); G_BAR; G_SCHED;
;       G_LDB(B1, 0, 1); G_STAGE(G_SB(0, 0), b2, voffB);
;       G_BAR; G_WAIT_L(0); G_MMA(0, 1, At, B1); G_BAR;
;       G_LDA(At, 0, 1); G_STAGE(G_SA(0, 0), a2, voffA);
;       G_BAR; G_WAIT_L(0); G_MMA(1, 0, At, B0); G_BAR; G_SCHED;
;       G_STAGE(G_SB(0, 1), b2 + hstepB, voffB);
;       G_WAIT_V(6); G_BAR; G_MMA(1, 1, At, B1); G_BAR;
.LBB0_282:
	s_add_i32 s1, s84, 0x100
	ds_read_b128 v[134:137], v208
	ds_read_b128 v[138:141], v208 offset:1024
	ds_read_b128 v[152:155], v208 offset:2048
	ds_read_b128 v[156:159], v208 offset:3072
	s_add_u32 s10, s9, s0
	s_addc_u32 s11, s19, 0
	ds_read_b128 v[160:163], v151
	ds_read_b128 v[164:167], v151 offset:1024
	ds_read_b128 v[168:171], v151 offset:2048
	ds_read_b128 v[172:175], v151 offset:3072
	ds_read_b128 v[176:179], v151 offset:4096
	ds_read_b128 v[180:183], v151 offset:5120
	ds_read_b128 v[184:187], v151 offset:6144
	ds_read_b128 v[188:191], v151 offset:7168
	s_waitcnt lgkmcnt(8)
	s_barrier
	s_waitcnt lgkmcnt(0)
	v_mfma_f32_16x16x32_bf16 v[124:127], v[134:137], v[160:163], v[124:127]
	v_mfma_f32_16x16x32_bf16 v[120:123], v[152:155], v[160:163], v[120:123]
	v_mfma_f32_16x16x32_bf16 v[108:111], v[134:137], v[168:171], v[108:111]
	v_mfma_f32_16x16x32_bf16 v[104:107], v[152:155], v[168:171], v[104:107]
	v_mfma_f32_16x16x32_bf16 v[92:95], v[134:137], v[176:179], v[92:95]
	v_mfma_f32_16x16x32_bf16 v[88:91], v[152:155], v[176:179], v[88:91]
	v_mfma_f32_16x16x32_bf16 v[76:79], v[134:137], v[184:187], v[76:79]
	v_mfma_f32_16x16x32_bf16 v[72:75], v[152:155], v[184:187], v[72:75]
	v_mfma_f32_16x16x32_bf16 v[124:127], v[138:141], v[164:167], v[124:127]
	v_mfma_f32_16x16x32_bf16 v[120:123], v[156:159], v[164:167], v[120:123]
	v_mfma_f32_16x16x32_bf16 v[108:111], v[138:141], v[172:175], v[108:111]
	v_mfma_f32_16x16x32_bf16 v[104:107], v[156:159], v[172:175], v[104:107]
	v_mfma_f32_16x16x32_bf16 v[92:95], v[138:141], v[180:183], v[92:95]
	v_mfma_f32_16x16x32_bf16 v[88:91], v[156:159], v[180:183], v[88:91]
	v_mfma_f32_16x16x32_bf16 v[76:79], v[138:141], v[188:191], v[76:79]
	v_mfma_f32_16x16x32_bf16 v[72:75], v[156:159], v[188:191], v[72:75]
	s_barrier
	s_add_i32 m0, s15, 0xc000
	s_nop 0
	global_load_lds_dwordx4 v128, s[10:11]
	s_add_i32 m0, s15, 0xe000
	s_nop 0
	global_load_lds_dwordx4 v130, s[10:11]
	s_add_i32 s0, s85, 0x100
	s_add_i32 s1, s1, s5
	ds_read_b128 v[192:195], v208 offset:16384
	ds_read_b128 v[196:199], v208 offset:17408
	ds_read_b128 v[200:203], v208 offset:18432
	ds_read_b128 v[204:207], v208 offset:19456
	s_mov_b32 m0, s1
	s_nop 0
	global_load_lds_dwordx4 v146, s[76:77]
	s_add_i32 m0, s1, 0x2000
	s_nop 0
	global_load_lds_dwordx4 v132, s[76:77]
	s_barrier
	s_waitcnt lgkmcnt(0)
	v_mfma_f32_16x16x32_bf16 v[116:119], v[192:195], v[160:163], v[116:119]
	v_mfma_f32_16x16x32_bf16 v[112:115], v[200:203], v[160:163], v[112:115]
	v_mfma_f32_16x16x32_bf16 v[100:103], v[192:195], v[168:171], v[100:103]
	v_mfma_f32_16x16x32_bf16 v[96:99], v[200:203], v[168:171], v[96:99]
	v_mfma_f32_16x16x32_bf16 v[84:87], v[192:195], v[176:179], v[84:87]
	v_mfma_f32_16x16x32_bf16 v[80:83], v[200:203], v[176:179], v[80:83]
	v_mfma_f32_16x16x32_bf16 v[68:71], v[192:195], v[184:187], v[68:71]
	v_mfma_f32_16x16x32_bf16 v[64:67], v[200:203], v[184:187], v[64:67]
	v_mfma_f32_16x16x32_bf16 v[116:119], v[196:199], v[164:167], v[116:119]
	v_mfma_f32_16x16x32_bf16 v[112:115], v[204:207], v[164:167], v[112:115]
	v_mfma_f32_16x16x32_bf16 v[100:103], v[196:199], v[172:175], v[100:103]
	v_mfma_f32_16x16x32_bf16 v[96:99], v[204:207], v[172:175], v[96:99]
	v_mfma_f32_16x16x32_bf16 v[84:87], v[196:199], v[180:183], v[84:87]
	v_mfma_f32_16x16x32_bf16 v[80:83], v[204:207], v[180:183], v[80:83]
	v_mfma_f32_16x16x32_bf16 v[68:71], v[196:199], v[188:191], v[68:71]
	v_mfma_f32_16x16x32_bf16 v[64:67], v[204:207], v[188:191], v[64:67]
	s_mov_b32 m0, s15
	s_barrier
	ds_read_b128 v[160:163], v151 offset:16384
	ds_read_b128 v[164:167], v151 offset:17408
	ds_read_b128 v[168:171], v151 offset:18432
	ds_read_b128 v[172:175], v151 offset:19456
	ds_read_b128 v[176:179], v151 offset:20480
	ds_read_b128 v[180:183], v151 offset:21504
	ds_read_b128 v[184:187], v151 offset:22528
	ds_read_b128 v[188:191], v151 offset:23552
	global_load_lds_dwordx4 v128, s[74:75]
	s_mov_b32 m0, s24
	s_nop 0
	global_load_lds_dwordx4 v130, s[74:75]
	s_barrier
	s_waitcnt lgkmcnt(0)
	v_mfma_f32_16x16x32_bf16 v[60:63], v[134:137], v[160:163], v[60:63]
	v_mfma_f32_16x16x32_bf16 v[56:59], v[152:155], v[160:163], v[56:59]
	v_mfma_f32_16x16x32_bf16 v[44:47], v[134:137], v[168:171], v[44:47]
	v_mfma_f32_16x16x32_bf16 v[40:43], v[152:155], v[168:171], v[40:43]
	v_mfma_f32_16x16x32_bf16 v[28:31], v[134:137], v[176:179], v[28:31]
	v_mfma_f32_16x16x32_bf16 v[24:27], v[152:155], v[176:179], v[24:27]
	v_mfma_f32_16x16x32_bf16 v[12:15], v[134:137], v[184:187], v[12:15]
	v_mfma_f32_16x16x32_bf16 v[8:11], v[152:155], v[184:187], v[8:11]
	v_mfma_f32_16x16x32_bf16 v[60:63], v[138:141], v[164:167], v[60:63]
	v_mfma_f32_16x16x32_bf16 v[56:59], v[156:159], v[164:167], v[56:59]
	v_mfma_f32_16x16x32_bf16 v[44:47], v[138:141], v[172:175], v[44:47]
	v_mfma_f32_16x16x32_bf16 v[40:43], v[156:159], v[172:175], v[40:43]
	v_mfma_f32_16x16x32_bf16 v[28:31], v[138:141], v[180:183], v[28:31]
	v_mfma_f32_16x16x32_bf16 v[24:27], v[156:159], v[180:183], v[24:27]
	v_mfma_f32_16x16x32_bf16 v[12:15], v[138:141], v[188:191], v[12:15]
	v_mfma_f32_16x16x32_bf16 v[8:11], v[156:159], v[188:191], v[8:11]
	s_barrier
	s_add_u32 s10, s76, 0x80000
	s_addc_u32 s11, s77, 0
	s_add_i32 s0, s0, s5
	s_mov_b32 m0, s0
	s_nop 0
	global_load_lds_dwordx4 v146, s[10:11]
	s_add_i32 m0, s0, 0x2000
	s_nop 0
	global_load_lds_dwordx4 v132, s[10:11]
	s_waitcnt vmcnt(6)
	s_barrier
; #define G_STAGE(bufoff, gbase, voff) do { _Pragma("unroll") for (int _i = 0; _i < 2; ++_i) \
;         __builtin_amdgcn_global_load_lds((const unsigned*)((const char*)(gbase) + (voff)[_i]), (LAS unsigned*)(lds + (bufoff) + ldsw + _i * 8192), 16, 0, 0); } while (0)
; #define G_LDA(dst, b, h) do { _Pragma("unroll") for (int m = 0; m < 4; ++m) _Pragma("unroll") for (int k = 0; k < 2; ++k) dst[m][k] = *(const LAS bf16x8*)(lds + G_SA(b, h) + aoff + m * 2048 + k * 1024); } while (0)
; #define G_LDB(dst, b, h) do { _Pragma("unroll") for (int n = 0; n < 2; ++n) _Pragma("unroll") for (int k = 0; k < 2; ++k) dst[n][k] = *(const LAS bf16x8*)(lds + G_SB(b, h) + boff + n * 2048 + k * 1024); } while (0)
; #define G_MMA(ai, bj, At, Bt) do { __builtin_amdgcn_s_setprio(1); _Pragma("unroll") for (int m = 0; m < 4; ++m) _Pragma("unroll") for (int n = 0; n < 2; ++n) _Pragma("unroll") for (int k = 0; k < 2; ++k) \
;         acc[ai][bj][m][n] = __builtin_amdgcn_mfma_f32_16x16x32_bf16(Bt[n][k], At[m][k], acc[ai][bj][m][n], 0, 0, 0); __builtin_amdgcn_s_setprio(0); } while (0)
; #define G_WAIT_V(n) asm volatile("s_waitcnt vmcnt(" #n ")" ::: "memory")
; #define G_WAIT_L(n) asm volatile("s_waitcnt lgkmcnt(" #n ")" ::: "memory")
; #define G_BAR __builtin_amdgcn_s_barrier()
; #define G_SCHED __builtin_amdgcn_sched_barrier(0)
; template <class J>
; DI void gemm_phase(LAS unsigned char* lds, const J& job) {
;     ...
;       G_WAIT_V(6); G_BAR; G_MMA(1, 1, At, B1); G_BAR;
;       G_LDB(B0, 1, 0); G_SCHED; G_LDA(At, 1, 0); G_STAGE(G_SA(0, 1), a2 + hstepA, voffA);
;       G_WAIT_L(8); G_BAR; G_WAIT_L(0); G_MMA(0, 0, At, B0); G_BAR; G_SCHED;
;       G_LDB(B1, 1, 1); G_STAGE(G_SB(1, 0), b3, voffB);
;       G_BAR; G_WAIT_L(0); G_MMA(0, 1, At, B1); G_BAR;
;       G_LDA(At, 1, 1); G_STAGE(G_SA(1, 0), a3, voffA);
;       G_BAR; G_WAIT_L(0); G_MMA(1, 0, At, B0); G_BAR; G_SCHED;
	v_mfma_f32_16x16x32_bf16 v[52:55], v[192:195], v[160:163], v[52:55]
	v_mfma_f32_16x16x32_bf16 v[48:51], v[200:203], v[160:163], v[48:51]
	v_mfma_f32_16x16x32_bf16 v[36:39], v[192:195], v[168:171], v[36:39]
	v_mfma_f32_16x16x32_bf16 v[32:35], v[200:203], v[168:171], v[32:35]
	v_mfma_f32_16x16x32_bf16 v[20:23], v[192:195], v[176:179], v[20:23]
	v_mfma_f32_16x16x32_bf16 v[16:19], v[200:203], v[176:179], v[16:19]
	v_mfma_f32_16x16x32_bf16 v[4:7], v[192:195], v[184:187], v[4:7]
	v_mfma_f32_16x16x32_bf16 v[0:3], v[200:203], v[184:187], v[0:3]
	v_mfma_f32_16x16x32_bf16 v[52:55], v[196:199], v[164:167], v[52:55]
	v_mfma_f32_16x16x32_bf16 v[48:51], v[204:207], v[164:167], v[48:51]
	v_mfma_f32_16x16x32_bf16 v[36:39], v[196:199], v[172:175], v[36:39]
	v_mfma_f32_16x16x32_bf16 v[32:35], v[204:207], v[172:175], v[32:35]
	v_mfma_f32_16x16x32_bf16 v[20:23], v[196:199], v[180:183], v[20:23]
	v_mfma_f32_16x16x32_bf16 v[16:19], v[204:207], v[180:183], v[16:19]
	v_mfma_f32_16x16x32_bf16 v[4:7], v[196:199], v[188:191], v[4:7]
	v_mfma_f32_16x16x32_bf16 v[0:3], v[204:207], v[188:191], v[0:3]
	s_add_i32 s0, s88, 0x100
	s_barrier
	ds_read_b128 v[134:137], v208 offset:32768
	ds_read_b128 v[138:141], v208 offset:33792
	ds_read_b128 v[152:155], v208 offset:34816
	ds_read_b128 v[156:159], v208 offset:35840
	s_add_u32 s10, s74, 0x80000
	s_addc_u32 s11, s75, 0
	ds_read_b128 v[160:163], v151 offset:32768
	ds_read_b128 v[164:167], v151 offset:33792
	ds_read_b128 v[168:171], v151 offset:34816
	ds_read_b128 v[172:175], v151 offset:35840
	ds_read_b128 v[176:179], v151 offset:36864
	ds_read_b128 v[180:183], v151 offset:37888
	ds_read_b128 v[184:187], v151 offset:38912
	ds_read_b128 v[188:191], v151 offset:39936
	s_waitcnt lgkmcnt(8)
	s_barrier
	s_waitcnt lgkmcnt(0)
	v_mfma_f32_16x16x32_bf16 v[124:127], v[134:137], v[160:163], v[124:127]
	v_mfma_f32_16x16x32_bf16 v[120:123], v[152:155], v[160:163], v[120:123]
	v_mfma_f32_16x16x32_bf16 v[108:111], v[134:137], v[168:171], v[108:111]
	v_mfma_f32_16x16x32_bf16 v[104:107], v[152:155], v[168:171], v[104:107]
	v_mfma_f32_16x16x32_bf16 v[92:95], v[134:137], v[176:179], v[92:95]
	v_mfma_f32_16x16x32_bf16 v[88:91], v[152:155], v[176:179], v[88:91]
	v_mfma_f32_16x16x32_bf16 v[76:79], v[134:137], v[184:187], v[76:79]
	v_mfma_f32_16x16x32_bf16 v[72:75], v[152:155], v[184:187], v[72:75]
	v_mfma_f32_16x16x32_bf16 v[124:127], v[138:141], v[164:167], v[124:127]
	v_mfma_f32_16x16x32_bf16 v[120:123], v[156:159], v[164:167], v[120:123]
	v_mfma_f32_16x16x32_bf16 v[108:111], v[138:141], v[172:175], v[108:111]
	v_mfma_f32_16x16x32_bf16 v[104:107], v[156:159], v[172:175], v[104:107]
	v_mfma_f32_16x16x32_bf16 v[92:95], v[138:141], v[180:183], v[92:95]
	v_mfma_f32_16x16x32_bf16 v[88:91], v[156:159], v[180:183], v[88:91]
	v_mfma_f32_16x16x32_bf16 v[76:79], v[138:141], v[188:191], v[76:79]
	v_mfma_f32_16x16x32_bf16 v[72:75], v[156:159], v[188:191], v[72:75]
	s_barrier
	s_mov_b32 m0, s25
	s_nop 0
	global_load_lds_dwordx4 v128, s[10:11]
	s_mov_b32 m0, s36
	s_nop 0
	global_load_lds_dwordx4 v130, s[10:11]
	s_add_i32 s1, s89, 0x100
	s_add_i32 s0, s0, s5
	ds_read_b128 v[192:195], v208 offset:49152
	ds_read_b128 v[196:199], v208 offset:50176
	ds_read_b128 v[200:203], v208 offset:51200
	ds_read_b128 v[204:207], v208 offset:52224
	s_mov_b32 m0, s0
	s_nop 0
	global_load_lds_dwordx4 v146, s[70:71]
	s_add_i32 m0, s0, 0x2000
	s_nop 0
	global_load_lds_dwordx4 v132, s[70:71]
	s_barrier
	s_waitcnt lgkmcnt(0)
	v_mfma_f32_16x16x32_bf16 v[116:119], v[192:195], v[160:163], v[116:119]
	v_mfma_f32_16x16x32_bf16 v[112:115], v[200:203], v[160:163], v[112:115]
	v_mfma_f32_16x16x32_bf16 v[100:103], v[192:195], v[168:171], v[100:103]
	v_mfma_f32_16x16x32_bf16 v[96:99], v[200:203], v[168:171], v[96:99]
	v_mfma_f32_16x16x32_bf16 v[84:87], v[192:195], v[176:179], v[84:87]
	v_mfma_f32_16x16x32_bf16 v[80:83], v[200:203], v[176:179], v[80:83]
	v_mfma_f32_16x16x32_bf16 v[68:71], v[192:195], v[184:187], v[68:71]
	v_mfma_f32_16x16x32_bf16 v[64:67], v[200:203], v[184:187], v[64:67]
	v_mfma_f32_16x16x32_bf16 v[116:119], v[196:199], v[164:167], v[116:119]
	v_mfma_f32_16x16x32_bf16 v[112:115], v[204:207], v[164:167], v[112:115]
	v_mfma_f32_16x16x32_bf16 v[100:103], v[196:199], v[172:175], v[100:103]
	v_mfma_f32_16x16x32_bf16 v[96:99], v[204:207], v[172:175], v[96:99]
	v_mfma_f32_16x16x32_bf16 v[84:87], v[196:199], v[180:183], v[84:87]
	v_mfma_f32_16x16x32_bf16 v[80:83], v[204:207], v[180:183], v[80:83]
	v_mfma_f32_16x16x32_bf16 v[68:71], v[196:199], v[188:191], v[68:71]
	v_mfma_f32_16x16x32_bf16 v[64:67], v[204:207], v[188:191], v[64:67]
	s_mov_b32 m0, s45
	s_barrier
; DI unsigned pk2(float lo, float hi) { unsigned r; asm("v_cvt_pk_bf16_f32 %0, %1, %2" : "=v"(r) : "v"(lo), "v"(hi)); return r; }
; #define G_STAGE(bufoff, gbase, voff) do { _Pragma("unroll") for (int _i = 0; _i < 2; ++_i) \
;         __builtin_amdgcn_global_load_lds((const unsigned*)((const char*)(gbase) + (voff)[_i]), (LAS unsigned*)(lds + (bufoff) + ldsw + _i * 8192), 16, 0, 0); } while (0)
; #define G_LDA(dst, b, h) do { _Pragma("unroll") for (int m = 0; m < 4; ++m) _Pragma("unroll") for (int k = 0; k < 2; ++k) dst[m][k] = *(const LAS bf16x8*)(lds + G_SA(b, h) + aoff + m * 2048 + k * 1024); } while (0)
; #define G_LDB(dst, b, h) do { _Pragma("unroll") for (int n = 0; n < 2; ++n) _Pragma("unroll") for (int k = 0; k < 2; ++k) dst[n][k] = *(const LAS bf16x8*)(lds + G_SB(b, h) + boff + n * 2048 + k * 1024); } while (0)
; #define G_WAIT_V(n) asm volatile("s_waitcnt vmcnt(" #n ")" ::: "memory")
; #define G_WAIT_L(n) asm volatile("s_waitcnt lgkmcnt(" #n ")" ::: "memory")
; #define G_BAR __builtin_amdgcn_s_barrier()
; #define G_SCHED __builtin_amdgcn_sched_barrier(0)
; template <class J>
; DI void gemm_phase(LAS unsigned char* lds, const J& job) {
;     ...
;       G_LDB(B1, 1, 1); G_STAGE(G_SB(1, 0), b3, voffB);
;       G_BAR; G_WAIT_L(0); G_MMA(0, 1, At, B1); G_BAR;
;       G_LDA(At, 1, 1); G_STAGE(G_SA(1, 0), a3, voffA);
;       G_BAR; G_WAIT_L(0); G_MMA(1, 0, At, B0); G_BAR; G_SCHED;
;       G_STAGE(G_SB(1, 1), b3 + hstepB, voffB);
;       G_WAIT_V(6); G_BAR; G_MMA(1, 1, At, B1); G_BAR;
;   DI void epi(const Acc& acc, const Unit& u, int wr, int wc, int fr, int fq) const {
;     ...
;         const int rl = ai * HALF + wr * 64 + m * 16 + fr;
; #pragma unroll
;         for (int bj = 0; bj < 2; ++bj) {
;           const int col = u.pn * 256 + bj * HALF + wc * 32 + 8 * fq;
;           const f32x4 v0 = acc[ai][bj][m][0], v1 = acc[ai][bj][m][1];
;           const int row = u.pm * 256 + rl;
;           u32x4 o; o.x = pk2(v0.x, v0.y); o.y = pk2(v0.z, v0.w); o.z = pk2(v1.x, v1.y); o.w = pk2(v1.z, v1.w);
;           *(u32x4*)(proj + (size_t)row * NPROJ + col) = o;
;           if (u.pn >= 8 && u.pn < 12) {
;             const int isv = u.pn >= 10; const int cc = col - (isv ? C_BV : C_BK);
;             float* dst = out + (isv ? O_VP : O_KP) + ((size_t)l * TP + row) * 512 + cc;
;             *(f32x4*)dst = v0; *(f32x4*)(dst + 4) = v1;
	ds_read_b128 v[160:163], v151 offset:49152
	ds_read_b128 v[164:167], v151 offset:50176
	ds_read_b128 v[168:171], v151 offset:51200
	ds_read_b128 v[172:175], v151 offset:52224
	ds_read_b128 v[176:179], v151 offset:53248
	ds_read_b128 v[180:183], v151 offset:54272
	ds_read_b128 v[184:187], v151 offset:55296
	ds_read_b128 v[188:191], v151 offset:56320
	global_load_lds_dwordx4 v128, s[72:73]
	s_mov_b32 m0, s65
	s_nop 0
	global_load_lds_dwordx4 v130, s[72:73]
	s_barrier
	s_waitcnt lgkmcnt(0)
	v_mfma_f32_16x16x32_bf16 v[60:63], v[134:137], v[160:163], v[60:63]
	v_mfma_f32_16x16x32_bf16 v[56:59], v[152:155], v[160:163], v[56:59]
	v_mfma_f32_16x16x32_bf16 v[44:47], v[134:137], v[168:171], v[44:47]
	v_mfma_f32_16x16x32_bf16 v[40:43], v[152:155], v[168:171], v[40:43]
	v_mfma_f32_16x16x32_bf16 v[28:31], v[134:137], v[176:179], v[28:31]
	v_mfma_f32_16x16x32_bf16 v[24:27], v[152:155], v[176:179], v[24:27]
	v_mfma_f32_16x16x32_bf16 v[12:15], v[134:137], v[184:187], v[12:15]
	v_mfma_f32_16x16x32_bf16 v[8:11], v[152:155], v[184:187], v[8:11]
	v_mfma_f32_16x16x32_bf16 v[60:63], v[138:141], v[164:167], v[60:63]
	v_mfma_f32_16x16x32_bf16 v[56:59], v[156:159], v[164:167], v[56:59]
	v_mfma_f32_16x16x32_bf16 v[44:47], v[138:141], v[172:175], v[44:47]
	v_mfma_f32_16x16x32_bf16 v[40:43], v[156:159], v[172:175], v[40:43]
	v_mfma_f32_16x16x32_bf16 v[28:31], v[138:141], v[180:183], v[28:31]
	v_mfma_f32_16x16x32_bf16 v[24:27], v[156:159], v[180:183], v[24:27]
	v_mfma_f32_16x16x32_bf16 v[12:15], v[138:141], v[188:191], v[12:15]
	v_mfma_f32_16x16x32_bf16 v[8:11], v[156:159], v[188:191], v[8:11]
	s_barrier
	s_add_u32 s10, s70, 0x80000
	s_addc_u32 s11, s71, 0
	s_add_i32 s0, s1, s5
	s_mov_b32 m0, s0
	s_nop 0
	global_load_lds_dwordx4 v146, s[10:11]
	s_add_i32 m0, s0, 0x2000
	s_nop 0
	global_load_lds_dwordx4 v132, s[10:11]
	s_add_i32 s6, s6, 2
	s_addk_i32 s56, 0x100
	s_addk_i32 s7, 0x100
	s_add_i32 s1, s56, 0xffffff80
	s_and_b32 s0, s7, 0xf80
	s_and_b32 s1, s1, 0xf00
	s_add_u32 s10, s68, s1
	s_addc_u32 s11, s69, 0
	s_add_u32 s1, s66, s1
	s_addc_u32 s57, s67, 0
	s_and_b32 s70, s56, 0xf80
	s_add_u32 s71, s68, s70
	s_addc_u32 s72, s69, 0
	s_add_u32 s70, s66, s70
	s_addc_u32 s80, s67, 0
	s_cmp_eq_u32 s6, 28
	s_cselect_b32 s75, s46, s11
	s_cselect_b32 s74, s21, s10
	s_cselect_b32 s77, s96, s57
	s_cselect_b32 s76, s47, s1
	s_cselect_b32 s73, s97, s72
	s_cselect_b32 s72, s33, s71
	s_cselect_b32 s71, vcc_hi, s80
	s_cselect_b32 s70, vcc_lo, s70
	s_waitcnt vmcnt(6)
	s_barrier
	v_mfma_f32_16x16x32_bf16 v[52:55], v[192:195], v[160:163], v[52:55]
	v_mfma_f32_16x16x32_bf16 v[48:51], v[200:203], v[160:163], v[48:51]
	v_mfma_f32_16x16x32_bf16 v[36:39], v[192:195], v[168:171], v[36:39]
	v_mfma_f32_16x16x32_bf16 v[32:35], v[200:203], v[168:171], v[32:35]
	v_mfma_f32_16x16x32_bf16 v[20:23], v[192:195], v[176:179], v[20:23]
	v_mfma_f32_16x16x32_bf16 v[16:19], v[200:203], v[176:179], v[16:19]
	v_mfma_f32_16x16x32_bf16 v[4:7], v[192:195], v[184:187], v[4:7]
	v_mfma_f32_16x16x32_bf16 v[0:3], v[200:203], v[184:187], v[0:3]
	v_mfma_f32_16x16x32_bf16 v[52:55], v[196:199], v[164:167], v[52:55]
	v_mfma_f32_16x16x32_bf16 v[48:51], v[204:207], v[164:167], v[48:51]
	v_mfma_f32_16x16x32_bf16 v[36:39], v[196:199], v[172:175], v[36:39]
	v_mfma_f32_16x16x32_bf16 v[32:35], v[204:207], v[172:175], v[32:35]
	v_mfma_f32_16x16x32_bf16 v[20:23], v[196:199], v[180:183], v[20:23]
	v_mfma_f32_16x16x32_bf16 v[16:19], v[204:207], v[180:183], v[16:19]
	v_mfma_f32_16x16x32_bf16 v[4:7], v[196:199], v[188:191], v[4:7]
	v_mfma_f32_16x16x32_bf16 v[0:3], v[204:207], v[188:191], v[0:3]
	s_cmp_gt_u32 s6, 29
	s_barrier
	s_cbranch_scc0 .LBB0_282
	v_mov_b32_e32 v135, v148
	v_mov_b32_e32 v134, v149
	s_lshl_b32 s0, s64, 8
	s_or_b32 s0, s0, s38
	v_lshl_add_u32 v134, v134, 3, s0
	s_lshl_b32 s0, s8, 8
	s_add_i32 s0, s0, s37
	v_add_u32_e32 v136, s0, v135
	s_and_b32 s0, s64, -4
	s_cmp_eq_u32 s0, 8
	s_cselect_b64 s[66:67], -1, 0
	s_cmp_gt_u32 s64, 9
	s_cselect_b64 s[6:7], -1, 0
	s_and_b64 s[6:7], s[6:7], exec
	s_movk_i32 s1, 0xf600
	v_mov_b64_e32 v[138:139], s[26:27]
	s_cselect_b32 s7, s1, 0xfffff800
	s_mov_b32 s1, 0x3040000
	v_ashrrev_i32_e32 v137, 31, v136
	v_mad_i64_i32 v[138:139], s[8:9], v136, s92, v[138:139]
	v_ashrrev_i32_e32 v135, 31, v134
	s_cselect_b32 s6, s1, 0x2040000
	s_cmp_lg_u32 s0, 8
	v_lshlrev_b64 v[140:141], 11, v[136:137]
	v_lshl_add_u64 v[142:143], v[134:135], 1, v[138:139]
	v_add_u32_e32 v138, s7, v134
	v_cvt_pk_bf16_f32 v152, v124, v125
	v_cvt_pk_bf16_f32 v153, v126, v127
	v_cvt_pk_bf16_f32 v154, v120, v121
	v_cvt_pk_bf16_f32 v155, v122, v123
	global_store_dwordx4 v[142:143], v[152:155], off
	s_cbranch_scc1 .LBB0_285
	s_lshl_b32 s0, s6, 2
	s_add_u32 s8, s83, s0
	s_addc_u32 s9, s86, 0
	v_lshl_add_u64 v[152:153], s[8:9], 0, v[140:141]
	v_ashrrev_i32_e32 v139, 31, v138
	v_lshl_add_u64 v[152:153], v[138:139], 2, v[152:153]
	global_store_dwordx4 v[152:153], v[124:127], off
	global_store_dwordx4 v[152:153], v[120:123], off offset:16
